# ssm_s3: hoist the 8 skip-connection u loads of each item to one burst with counted vmcnt (on top of attention v2)
# baseline (speedup 1.0000x reference)
; #define LAS __attribute__((address_space(3)))
; DI unsigned f2bf(float f) { unsigned u = __builtin_bit_cast(unsigned, f); return (u + 0x7fffu + ((u >> 16) & 1u)) >> 16; }
; DI void ssm_step_lds(const SsmC& c, const LAS bf16_t* up_, float& xr, float& xi) {
;     const LAS f32x4* up = (const LAS f32x4*)up_;
;     const f32x4 u0 = up[0], u1 = up[1], u2 = up[2], u3 = up[3];
;     float sr = 0.f, si = 0.f;
; #pragma unroll
;     for (int e = 0; e < 4; ++e) { sr += c.bbr[e] * u0[e]; si += c.bbi[e] * u0[e]; }
; #pragma unroll
;     for (int e = 0; e < 4; ++e) { sr += c.bbr[4 + e] * u1[e]; si += c.bbi[4 + e] * u1[e]; }
; #pragma unroll
;     for (int e = 0; e < 4; ++e) { sr += c.bbr[8 + e] * u2[e]; si += c.bbi[8 + e] * u2[e]; }
; #pragma unroll
;     for (int e = 0; e < 4; ++e) { sr += c.bbr[12 + e] * u3[e]; si += c.bbi[12 + e] * u3[e]; }
;     const float nxr = c.ar * xr - c.ai * xi + sr, nxi = c.ar * xi + c.ai * xr + si; xr = nxr; xi = nxi;
; }
; DI void ssm_s3(CArgs& a, int l, int it, int lane, LAS bf16_t* Xs  , LAS bf16_t* Us) {
;     ...
;         for (int tt = 0; tt < 32; ++tt) { ssm_step_lds(c, Us + (32 * sub + tt) * 32, xr, xi);
;             Xs[tt * 136 + lane] = (bf16_t)f2bf(xr); Xs[tt * 136 + 64 + lane] = (bf16_t)f2bf(xi); }
.LBB0_180:
	s_add_i32 s4, s0, s3
	s_add_i32 s5, s4, 0x11800
	v_mov_b32_e32 v4, s5
	ds_read_b128 v[42:45], v4
	s_add_i32 s5, s4, 0x11810
	v_mov_b32_e32 v4, s5
	s_add_i32 s5, s4, 0x11820
	ds_read_b128 v[46:49], v4
	v_mov_b32_e32 v4, s5
	s_add_i32 s5, s4, 0x11830
	ds_read_b128 v[50:53], v4
	v_mov_b32_e32 v4, s5
	ds_read_b128 v[128:131], v4
	s_waitcnt lgkmcnt(3)
	v_pk_fma_f32 v[4:5], v[74:75], v[42:43], 0 op_sel_hi:[1,0,0]
	s_add_i32 s5, s4, 0x11840
	v_pk_fma_f32 v[4:5], v[76:77], v[42:43], v[4:5] op_sel:[0,1,0]
	v_mov_b32_e32 v42, v45
	v_pk_fma_f32 v[4:5], v[78:79], v[44:45], v[4:5] op_sel_hi:[1,0,1]
	s_waitcnt lgkmcnt(0)
	v_mov_b32_e32 v44, v131
	v_pk_fma_f32 v[4:5], v[98:99], v[42:43], v[4:5] op_sel_hi:[1,0,1]
	v_mov_b32_e32 v42, v49
	v_pk_fma_f32 v[4:5], v[100:101], v[46:47], v[4:5] op_sel_hi:[1,0,1]
	s_addk_i32 s3, 0x100
	v_pk_fma_f32 v[4:5], v[102:103], v[46:47], v[4:5] op_sel:[0,1,0]
	s_nop 0
	v_pk_fma_f32 v[4:5], v[104:105], v[48:49], v[4:5] op_sel_hi:[1,0,1]
	s_nop 0
	v_pk_fma_f32 v[4:5], v[106:107], v[42:43], v[4:5] op_sel_hi:[1,0,1]
	v_mov_b32_e32 v42, v53
	v_pk_fma_f32 v[4:5], v[108:109], v[50:51], v[4:5] op_sel_hi:[1,0,1]
	s_nop 0
	v_pk_fma_f32 v[4:5], v[110:111], v[50:51], v[4:5] op_sel:[0,1,0]
	s_nop 0
	v_pk_fma_f32 v[4:5], v[112:113], v[52:53], v[4:5] op_sel_hi:[1,0,1]
	s_nop 0
	v_pk_fma_f32 v[4:5], v[114:115], v[42:43], v[4:5] op_sel_hi:[1,0,1]
	v_pk_mul_f32 v[42:43], v[72:73], v[38:39]
	v_pk_fma_f32 v[4:5], v[116:117], v[128:129], v[4:5] op_sel_hi:[1,0,1]
	s_nop 0
	v_pk_fma_f32 v[4:5], v[118:119], v[128:129], v[4:5] op_sel:[0,1,0]
	s_nop 0
	v_pk_fma_f32 v[4:5], v[120:121], v[130:131], v[4:5] op_sel_hi:[1,0,1]
	s_nop 0
	v_pk_fma_f32 v[4:5], v[122:123], v[44:45], v[4:5] op_sel_hi:[1,0,1]
	v_pk_fma_f32 v[44:45], v[70:71], v[38:39], v[42:43] op_sel:[0,0,1] op_sel_hi:[1,1,0]
	v_pk_fma_f32 v[38:39], v[70:71], v[38:39], v[42:43] op_sel:[0,0,1] op_sel_hi:[1,1,0] neg_lo:[0,0,1] neg_hi:[0,0,1]
	s_nop 0
	v_mov_b32_e32 v45, v39
	v_pk_add_f32 v[4:5], v[44:45], v[4:5]
	s_nop 0
	v_bfe_u32 v38, v5, 16, 1
	v_add3_u32 v38, v5, v38, s33
	ds_write_b16_d16_hi v40, v38
	v_bfe_u32 v38, v4, 16, 1
	v_add3_u32 v38, v4, v38, s33
	ds_write_b16_d16_hi v40, v38 offset:128
	v_mov_b32_e32 v38, s5
	ds_read_b128 v[42:45], v38
	s_add_i32 s5, s4, 0x11850
	v_mov_b32_e32 v38, s5
	s_add_i32 s5, s4, 0x11860
	ds_read_b128 v[46:49], v38
	v_mov_b32_e32 v38, s5
	s_add_i32 s5, s4, 0x11870
	ds_read_b128 v[50:53], v38
	v_mov_b32_e32 v38, s5
	ds_read_b128 v[128:131], v38
	s_waitcnt lgkmcnt(3)
	v_pk_fma_f32 v[38:39], v[74:75], v[42:43], 0 op_sel_hi:[1,0,0]
	s_add_i32 s5, s4, 0x11880
	v_pk_fma_f32 v[38:39], v[76:77], v[42:43], v[38:39] op_sel:[0,1,0]
	v_mov_b32_e32 v42, v45
	v_pk_fma_f32 v[38:39], v[78:79], v[44:45], v[38:39] op_sel_hi:[1,0,1]
	s_waitcnt lgkmcnt(0)
	v_mov_b32_e32 v44, v131
	v_pk_fma_f32 v[38:39], v[98:99], v[42:43], v[38:39] op_sel_hi:[1,0,1]
	v_mov_b32_e32 v42, v49
	v_pk_fma_f32 v[38:39], v[100:101], v[46:47], v[38:39] op_sel_hi:[1,0,1]
	s_nop 0
	v_pk_fma_f32 v[38:39], v[102:103], v[46:47], v[38:39] op_sel:[0,1,0]
	s_nop 0
	v_pk_fma_f32 v[38:39], v[104:105], v[48:49], v[38:39] op_sel_hi:[1,0,1]
	s_nop 0
	v_pk_fma_f32 v[38:39], v[106:107], v[42:43], v[38:39] op_sel_hi:[1,0,1]
	v_mov_b32_e32 v42, v53
	v_pk_fma_f32 v[38:39], v[108:109], v[50:51], v[38:39] op_sel_hi:[1,0,1]
	s_nop 0
	v_pk_fma_f32 v[38:39], v[110:111], v[50:51], v[38:39] op_sel:[0,1,0]
	s_nop 0
	v_pk_fma_f32 v[38:39], v[112:113], v[52:53], v[38:39] op_sel_hi:[1,0,1]
	s_nop 0
	v_pk_fma_f32 v[38:39], v[114:115], v[42:43], v[38:39] op_sel_hi:[1,0,1]
	v_pk_mul_f32 v[42:43], v[72:73], v[4:5]
	v_pk_fma_f32 v[38:39], v[116:117], v[128:129], v[38:39] op_sel_hi:[1,0,1]
	s_nop 0
	v_pk_fma_f32 v[38:39], v[118:119], v[128:129], v[38:39] op_sel:[0,1,0]
	s_nop 0
	v_pk_fma_f32 v[38:39], v[120:121], v[130:131], v[38:39] op_sel_hi:[1,0,1]
	s_nop 0
	v_pk_fma_f32 v[38:39], v[122:123], v[44:45], v[38:39] op_sel_hi:[1,0,1]
	v_pk_fma_f32 v[44:45], v[70:71], v[4:5], v[42:43] op_sel:[0,0,1] op_sel_hi:[1,1,0]
	v_pk_fma_f32 v[4:5], v[70:71], v[4:5], v[42:43] op_sel:[0,0,1] op_sel_hi:[1,1,0] neg_lo:[0,0,1] neg_hi:[0,0,1]
	s_nop 0
	v_mov_b32_e32 v45, v5
	v_pk_add_f32 v[4:5], v[44:45], v[38:39]
	s_nop 0
	v_bfe_u32 v38, v5, 16, 1
	v_add3_u32 v38, v5, v38, s33
	ds_write_b16_d16_hi v40, v38 offset:272
	v_bfe_u32 v38, v4, 16, 1
	v_add3_u32 v38, v4, v38, s33
	ds_write_b16_d16_hi v40, v38 offset:400
	v_mov_b32_e32 v38, s5
	ds_read_b128 v[42:45], v38
	s_add_i32 s5, s4, 0x11890
	v_mov_b32_e32 v38, s5
	s_add_i32 s5, s4, 0x118a0
	ds_read_b128 v[46:49], v38
	v_mov_b32_e32 v38, s5
	s_add_i32 s5, s4, 0x118b0
	ds_read_b128 v[50:53], v38
	v_mov_b32_e32 v38, s5
	ds_read_b128 v[128:131], v38
	s_waitcnt lgkmcnt(3)
	v_pk_fma_f32 v[38:39], v[74:75], v[42:43], 0 op_sel_hi:[1,0,0]
	s_add_i32 s5, s4, 0x118c0
	v_pk_fma_f32 v[38:39], v[76:77], v[42:43], v[38:39] op_sel:[0,1,0]
	v_mov_b32_e32 v42, v45
	v_pk_fma_f32 v[38:39], v[78:79], v[44:45], v[38:39] op_sel_hi:[1,0,1]
	s_waitcnt lgkmcnt(0)
; DI unsigned f2bf(float f) { unsigned u = __builtin_bit_cast(unsigned, f); return (u + 0x7fffu + ((u >> 16) & 1u)) >> 16; }
; DI unsigned pk2(float lo, float hi) { f32x2 v = {lo, hi}; bf16x2_t b = __builtin_convertvector(v, bf16x2_t); return __builtin_bit_cast(unsigned, b); }
; #define MFMA16(a, b, c) __builtin_amdgcn_mfma_f32_16x16x32_bf16((a), (b), (c), 0, 0, 0)
; DI void ssm_s3(CArgs& a, int l, int it, int lane, LAS bf16_t* Xs  , LAS bf16_t* Us) {
;     ...
;     for (int kk = 0; kk < 4; ++kk) { const int k = 32 * kk + 8 * fq; const bool im = k >= 64;
;         const float* src = (im ? a.in[I_CIM] : a.in[I_CRE]) + ((size_t)((l * 32 + g) * 16 + fr)) * 64 + (k & 63);
;         const f32x4 v0 = *(const f32x4*)src, v1 = *(const f32x4*)(src + 4); const float sg = im ? -1.f : 1.f;
;         u32x4 w; w.x = pk2(sg * v0[0], sg * v0[1]); w.y = pk2(sg * v0[2], sg * v0[3]); w.z = pk2(sg * v1[0], sg * v1[1]); w.w = pk2(sg * v1[2], sg * v1[3]);
;         cf[kk] = __builtin_bit_cast(bf16x8, w); }
;     ...
;         for (int tt = 0; tt < 32; ++tt) { ssm_step_lds(c, Us + (32 * sub + tt) * 32, xr, xi);
;             Xs[tt * 136 + lane] = (bf16_t)f2bf(xr); Xs[tt * 136 + 64 + lane] = (bf16_t)f2bf(xi); }
;         asm volatile("s_waitcnt lgkmcnt(0)" ::: "memory");
; #pragma unroll
;         for (int m = 0; m < 2; ++m) {
;             float zz = 0.f; asm volatile("" : "+v"(zz)); f32x4 acc = {zz, zz, zz, zz};
; #pragma unroll
;             for (int kk = 0; kk < 4; ++kk) { const bf16x8 xf = lds_b128(Xs + (16 * m + fr) * 136 + 32 * kk + 8 * fq); acc = MFMA16(cf[kk], xf, acc); }
	v_mov_b32_e32 v44, v131
	v_pk_fma_f32 v[38:39], v[98:99], v[42:43], v[38:39] op_sel_hi:[1,0,1]
	v_mov_b32_e32 v42, v49
	v_pk_fma_f32 v[38:39], v[100:101], v[46:47], v[38:39] op_sel_hi:[1,0,1]
	s_nop 0
	v_pk_fma_f32 v[38:39], v[102:103], v[46:47], v[38:39] op_sel:[0,1,0]
	s_nop 0
	v_pk_fma_f32 v[38:39], v[104:105], v[48:49], v[38:39] op_sel_hi:[1,0,1]
	s_nop 0
	v_pk_fma_f32 v[38:39], v[106:107], v[42:43], v[38:39] op_sel_hi:[1,0,1]
	v_mov_b32_e32 v42, v53
	v_pk_fma_f32 v[38:39], v[108:109], v[50:51], v[38:39] op_sel_hi:[1,0,1]
	s_nop 0
	v_pk_fma_f32 v[38:39], v[110:111], v[50:51], v[38:39] op_sel:[0,1,0]
	s_nop 0
	v_pk_fma_f32 v[38:39], v[112:113], v[52:53], v[38:39] op_sel_hi:[1,0,1]
	s_nop 0
	v_pk_fma_f32 v[38:39], v[114:115], v[42:43], v[38:39] op_sel_hi:[1,0,1]
	v_pk_mul_f32 v[42:43], v[72:73], v[4:5]
	v_pk_fma_f32 v[38:39], v[116:117], v[128:129], v[38:39] op_sel_hi:[1,0,1]
	s_nop 0
	v_pk_fma_f32 v[38:39], v[118:119], v[128:129], v[38:39] op_sel:[0,1,0]
	s_nop 0
	v_pk_fma_f32 v[38:39], v[120:121], v[130:131], v[38:39] op_sel_hi:[1,0,1]
	s_nop 0
	v_pk_fma_f32 v[38:39], v[122:123], v[44:45], v[38:39] op_sel_hi:[1,0,1]
	v_pk_fma_f32 v[44:45], v[70:71], v[4:5], v[42:43] op_sel:[0,0,1] op_sel_hi:[1,1,0]
	v_pk_fma_f32 v[4:5], v[70:71], v[4:5], v[42:43] op_sel:[0,0,1] op_sel_hi:[1,1,0] neg_lo:[0,0,1] neg_hi:[0,0,1]
	s_nop 0
	v_mov_b32_e32 v45, v5
	v_pk_add_f32 v[4:5], v[44:45], v[38:39]
	s_nop 0
	v_bfe_u32 v38, v5, 16, 1
	v_add3_u32 v38, v5, v38, s33
	ds_write_b16_d16_hi v40, v38 offset:544
	v_bfe_u32 v38, v4, 16, 1
	v_add3_u32 v38, v4, v38, s33
	ds_write_b16_d16_hi v40, v38 offset:672
	v_mov_b32_e32 v38, s5
	ds_read_b128 v[42:45], v38
	s_add_i32 s5, s4, 0x118d0
	v_mov_b32_e32 v38, s5
	s_add_i32 s5, s4, 0x118e0
	ds_read_b128 v[46:49], v38
	v_mov_b32_e32 v38, s5
	s_add_i32 s4, s4, 0x118f0
	ds_read_b128 v[50:53], v38
	v_mov_b32_e32 v38, s4
	ds_read_b128 v[128:131], v38
	s_waitcnt lgkmcnt(3)
	v_pk_fma_f32 v[38:39], v[74:75], v[42:43], 0 op_sel_hi:[1,0,0]
	s_cmp_eq_u32 s3, 0
	v_pk_fma_f32 v[38:39], v[76:77], v[42:43], v[38:39] op_sel:[0,1,0]
	v_mov_b32_e32 v42, v45
	v_pk_fma_f32 v[38:39], v[78:79], v[44:45], v[38:39] op_sel_hi:[1,0,1]
	s_waitcnt lgkmcnt(0)
	v_mov_b32_e32 v44, v131
	v_pk_fma_f32 v[38:39], v[98:99], v[42:43], v[38:39] op_sel_hi:[1,0,1]
	v_mov_b32_e32 v42, v49
	v_pk_fma_f32 v[38:39], v[100:101], v[46:47], v[38:39] op_sel_hi:[1,0,1]
	s_nop 0
	v_pk_fma_f32 v[38:39], v[102:103], v[46:47], v[38:39] op_sel:[0,1,0]
	s_nop 0
	v_pk_fma_f32 v[38:39], v[104:105], v[48:49], v[38:39] op_sel_hi:[1,0,1]
	s_nop 0
	v_pk_fma_f32 v[38:39], v[106:107], v[42:43], v[38:39] op_sel_hi:[1,0,1]
	v_mov_b32_e32 v42, v53
	v_pk_fma_f32 v[38:39], v[108:109], v[50:51], v[38:39] op_sel_hi:[1,0,1]
	s_nop 0
	v_pk_fma_f32 v[38:39], v[110:111], v[50:51], v[38:39] op_sel:[0,1,0]
	s_nop 0
	v_pk_fma_f32 v[38:39], v[112:113], v[52:53], v[38:39] op_sel_hi:[1,0,1]
	s_nop 0
	v_pk_fma_f32 v[38:39], v[114:115], v[42:43], v[38:39] op_sel_hi:[1,0,1]
	v_pk_mul_f32 v[42:43], v[72:73], v[4:5]
	v_pk_fma_f32 v[38:39], v[116:117], v[128:129], v[38:39] op_sel_hi:[1,0,1]
	s_nop 0
	v_pk_fma_f32 v[38:39], v[118:119], v[128:129], v[38:39] op_sel:[0,1,0]
	s_nop 0
	v_pk_fma_f32 v[38:39], v[120:121], v[130:131], v[38:39] op_sel_hi:[1,0,1]
	s_nop 0
	v_pk_fma_f32 v[38:39], v[122:123], v[44:45], v[38:39] op_sel_hi:[1,0,1]
	v_pk_fma_f32 v[44:45], v[70:71], v[4:5], v[42:43] op_sel:[0,0,1] op_sel_hi:[1,1,0]
	v_pk_fma_f32 v[4:5], v[70:71], v[4:5], v[42:43] op_sel:[0,0,1] op_sel_hi:[1,1,0] neg_lo:[0,0,1] neg_hi:[0,0,1]
	s_nop 0
	v_mov_b32_e32 v45, v5
	v_pk_add_f32 v[38:39], v[44:45], v[38:39]
	s_nop 0
	v_bfe_u32 v4, v39, 16, 1
	v_add3_u32 v4, v39, v4, s33
	ds_write_b16_d16_hi v40, v4 offset:816
	v_bfe_u32 v4, v38, 16, 1
	v_add3_u32 v4, v38, v4, s33
	ds_write_b16_d16_hi v40, v4 offset:944
	v_add_u32_e32 v40, 0x440, v40
	s_cbranch_scc0 .LBB0_180
	v_xor_b32_e32 v19, 0x80000000, v19
	v_xor_b32_e32 v18, 0x80000000, v18
	v_cvt_pk_bf16_f32 v18, v18, v19
	v_xor_b32_e32 v19, 0x80000000, v20
	v_xor_b32_e32 v20, 0x80000000, v21
	v_cvt_pk_bf16_f32 v19, v19, v20
	v_mov_b32_e32 v20, v81
	v_cvt_pk_bf16_f32 v4, v34, v35
	v_cvt_pk_bf16_f32 v5, v36, v37
	v_cvt_pk_bf16_f32 v6, v6, v7
	v_cvt_pk_bf16_f32 v7, v8, v9
	v_cvt_pk_bf16_f32 v8, v30, v31
	v_cvt_pk_bf16_f32 v9, v32, v33
	v_xor_b32_e32 v15, 0x80000000, v15
	v_xor_b32_e32 v14, 0x80000000, v14
	s_waitcnt lgkmcnt(0)
	ds_read_b128 v[30:33], v126
	v_cvt_pk_bf16_f32 v14, v14, v15
	v_xor_b32_e32 v15, 0x80000000, v16
	v_xor_b32_e32 v16, 0x80000000, v17
	v_cvt_pk_bf16_f32 v15, v15, v16
	v_xor_b32_e32 v16, 0x80000000, v23
	v_xor_b32_e32 v17, 0x80000000, v22
	v_cvt_pk_bf16_f32 v16, v17, v16
	v_xor_b32_e32 v17, 0x80000000, v24
	v_xor_b32_e32 v22, 0x80000000, v25
	v_cvt_pk_bf16_f32 v17, v17, v22
	v_mov_b32_e32 v21, v20
	v_mov_b32_e32 v22, v20
	v_mov_b32_e32 v23, v20
	v_cvt_pk_bf16_f32 v10, v10, v11
	v_cvt_pk_bf16_f32 v11, v12, v13
	s_waitcnt lgkmcnt(0)
	v_mfma_f32_16x16x32_bf16 v[20:23], v[4:7], v[30:33], v[20:23]
	ds_read_b128 v[30:33], v126 offset:64
	v_xor_b32_e32 v12, 0x80000000, v27
	v_xor_b32_e32 v13, 0x80000000, v26
	v_cvt_pk_bf16_f32 v12, v13, v12
	v_xor_b32_e32 v13, 0x80000000, v28
	v_xor_b32_e32 v26, 0x80000000, v29
	v_cvt_pk_bf16_f32 v13, v13, v26
	s_waitcnt lgkmcnt(0)
	v_mfma_f32_16x16x32_bf16 v[20:23], v[8:11], v[30:33], v[20:23]
	ds_read_b128 v[30:33], v126 offset:128
	s_lshl_b32 s36, s1, 1
	s_lshl_b64 s[4:5], s[6:7], 7
	s_waitcnt lgkmcnt(0)
	v_mfma_f32_16x16x32_bf16 v[20:23], v[12:15], v[30:33], v[20:23]
	ds_read_b128 v[30:33], v126 offset:192
	v_lshl_add_u64 v[28:29], v[60:61], 0, s[36:37]
	v_or_b32_e32 v26, s4, v54
	s_waitcnt lgkmcnt(0)
; DI unsigned pk2(float lo, float hi) { f32x2 v = {lo, hi}; bf16x2_t b = __builtin_convertvector(v, bf16x2_t); return __builtin_bit_cast(unsigned, b); }
; DI float bflo(unsigned w) { return __uint_as_float(w << 16); }
; DI float bfhi(unsigned w) { return __uint_as_float(w & 0xffff0000u); }
; DI float geluf_(float x) { const float a = 0.7978845608028654f * (x + 0.044715f * x * x * x); const float t = 1.f - 2.f * __builtin_amdgcn_rcpf(__expf(2.f * a) + 1.f); return 0.5f * x * (1.f + t); }
; DI void ssm_s3(CArgs& a, int l, int it, int lane, LAS bf16_t* Xs  , LAS bf16_t* Us) {
;     ...
;             const size_t tg = t0 + 32 * sub + 16 * m + fr;
;             const u32x2 uw = *(const u32x2*)(zb + tg * NZ + ZU + g * 16 + 4 * fq);
;             const float y0 = geluf_(acc[0] + dsk[0] * bflo(uw.x)), y1 = geluf_(acc[1] + dsk[1] * bfhi(uw.x)), y2 = geluf_(acc[2] + dsk[2] * bflo(uw.y)), y3 = geluf_(acc[3] + dsk[3] * bfhi(uw.y));
;             u32x2 ow; ow.x = pk2(y0, y1); ow.y = pk2(y2, y3);
;             *(u32x2*)(gb + tg * 512 + g * 16 + 4 * fq) = ow;
	v_mfma_f32_16x16x32_bf16 v[20:23], v[16:19], v[30:33], v[20:23]
	v_mad_u64_u32 v[30:31], s[6:7], v26, s55, v[28:29]
	v_mad_i32_i24 v31, s5, v220, v31
	global_load_dwordx2 v[32:33], v[30:31], off
	s_mov_b32 s98, 0x1a000
	s_mov_b32 s99, 0
	v_lshl_add_u64 v[248:249], v[30:31], 0, s[98:99]
	global_load_dwordx2 v[234:235], v[248:249], off
	v_lshl_add_u64 v[248:249], v[248:249], 0, s[98:99]
	global_load_dwordx2 v[236:237], v[248:249], off
	v_lshl_add_u64 v[248:249], v[248:249], 0, s[98:99]
	global_load_dwordx2 v[238:239], v[248:249], off
	v_lshl_add_u64 v[248:249], v[248:249], 0, s[98:99]
	global_load_dwordx2 v[240:241], v[248:249], off
	v_lshl_add_u64 v[248:249], v[248:249], 0, s[98:99]
	global_load_dwordx2 v[242:243], v[248:249], off
	v_lshl_add_u64 v[248:249], v[248:249], 0, s[98:99]
	global_load_dwordx2 v[244:245], v[248:249], off
	v_lshl_add_u64 v[248:249], v[248:249], 0, s[98:99]
	global_load_dwordx2 v[246:247], v[248:249], off
	v_mov_b32_e32 v27, s5
	v_lshl_add_u64 v[24:25], v[62:63], 0, s[36:37]
	s_movk_i32 s1, 0xf800
	s_waitcnt vmcnt(7)
	v_lshlrev_b32_e32 v34, 16, v32
	v_and_b32_e32 v35, 0xffff0000, v32
	v_pk_fma_f32 v[20:21], v[0:1], v[34:35], v[20:21]
	s_nop 0
	v_mul_f32_e32 v32, 0x3d372713, v20
	v_mul_f32_e32 v32, v20, v32
	v_fma_f32 v32, v20, v32, v20
	v_mul_f32_e32 v32, 0x3f4c422a, v32
	v_add_f32_e32 v32, v32, v32
	v_mul_f32_e32 v32, 0x3fb8aa3b, v32
	v_exp_f32_e32 v32, v32
	s_nop 0
	v_add_f32_e32 v32, 1.0, v32
	v_rcp_f32_e32 v34, v32
	v_mul_f32_e32 v32, 0x3d372713, v21
	v_mul_f32_e32 v32, v21, v32
	v_fma_f32 v32, v21, v32, v21
	v_mul_f32_e32 v32, 0x3f4c422a, v32
	v_add_f32_e32 v32, v32, v32
	v_mul_f32_e32 v32, 0x3fb8aa3b, v32
	v_exp_f32_e32 v32, v32
	v_pk_mul_f32 v[20:21], v[20:21], 0.5 op_sel_hi:[1,0]
	v_add_f32_e32 v32, 1.0, v32
	v_rcp_f32_e32 v35, v32
	v_lshlrev_b32_e32 v32, 16, v33
	v_and_b32_e32 v33, 0xffff0000, v33
	v_pk_fma_f32 v[22:23], v[2:3], v[32:33], v[22:23]
	v_pk_fma_f32 v[34:35], v[34:35], 2.0, 1.0 op_sel_hi:[1,0,0] neg_lo:[1,0,0] neg_hi:[1,0,0]
	v_mul_f32_e32 v32, 0x3d372713, v22
	v_mul_f32_e32 v33, 0x3d372713, v23
	v_mul_f32_e32 v32, v22, v32
	v_mul_f32_e32 v33, v23, v33
	v_fma_f32 v32, v22, v32, v22
	v_fma_f32 v33, v23, v33, v23
	v_mul_f32_e32 v32, 0x3f4c422a, v32
	v_mul_f32_e32 v33, 0x3f4c422a, v33
	v_add_f32_e32 v32, v32, v32
	v_add_f32_e32 v33, v33, v33
	v_mul_f32_e32 v32, 0x3fb8aa3b, v32
	v_mul_f32_e32 v33, 0x3fb8aa3b, v33
	v_exp_f32_e32 v32, v32
	v_exp_f32_e32 v33, v33
	v_pk_add_f32 v[34:35], v[34:35], 1.0 op_sel_hi:[1,0]
	v_pk_mul_f32 v[22:23], v[22:23], 0.5 op_sel_hi:[1,0]
	v_add_f32_e32 v32, 1.0, v32
	v_add_f32_e32 v33, 1.0, v33
	v_rcp_f32_e32 v32, v32
	v_rcp_f32_e32 v33, v33
	v_pk_mul_f32 v[20:21], v[20:21], v[34:35]
	v_pk_fma_f32 v[32:33], v[32:33], 2.0, 1.0 op_sel_hi:[1,0,0] neg_lo:[1,0,0] neg_hi:[1,0,0]
	s_nop 0
	v_pk_add_f32 v[32:33], v[32:33], 1.0 op_sel_hi:[1,0]
	s_nop 0
	v_pk_mul_f32 v[22:23], v[22:23], v[32:33]
	v_cvt_pk_bf16_f32 v32, v20, v21
	v_lshlrev_b64 v[20:21], 10, v[26:27]
	v_cvt_pk_bf16_f32 v33, v22, v23
	v_lshl_add_u64 v[22:23], v[24:25], 0, v[20:21]
	global_store_dwordx2 v[22:23], v[32:33], off
	v_add_co_u32_e32 v22, vcc, s79, v30
	v_mov_b32_e32 v32, v81
	s_nop 0
	v_addc_co_u32_e32 v23, vcc, 0, v31, vcc
	ds_read_b128 v[40:43], v126 offset:4352
	v_mov_b32_e32 v33, v32
	v_mov_b32_e32 v34, v32
	v_mov_b32_e32 v35, v32
	s_waitcnt vmcnt(6)
	v_mov_b32_e32 v22, v234
	v_mov_b32_e32 v23, v235
	v_lshlrev_b32_e32 v30, 16, v22
	s_waitcnt lgkmcnt(0)
	v_mfma_f32_16x16x32_bf16 v[32:35], v[4:7], v[40:43], v[32:35]
	ds_read_b128 v[40:43], v126 offset:4416
	v_and_b32_e32 v31, 0xffff0000, v22
	s_waitcnt lgkmcnt(0)
	v_mfma_f32_16x16x32_bf16 v[32:35], v[8:11], v[40:43], v[32:35]
	ds_read_b128 v[40:43], v126 offset:4480
	s_waitcnt lgkmcnt(0)
	v_mfma_f32_16x16x32_bf16 v[32:35], v[12:15], v[40:43], v[32:35]
	ds_read_b128 v[40:43], v126 offset:4544
	s_waitcnt lgkmcnt(0)
	v_mfma_f32_16x16x32_bf16 v[32:35], v[16:19], v[40:43], v[32:35]
	s_nop 7
	v_pk_fma_f32 v[30:31], v[0:1], v[30:31], v[32:33]
	s_nop 0
	v_mul_f32_e32 v22, 0x3d372713, v30
	v_mul_f32_e32 v22, v30, v22
	v_fma_f32 v22, v30, v22, v30
	v_mul_f32_e32 v22, 0x3f4c422a, v22
	v_add_f32_e32 v22, v22, v22
	v_mul_f32_e32 v22, 0x3fb8aa3b, v22
	v_exp_f32_e32 v22, v22
	s_nop 0
	v_add_f32_e32 v22, 1.0, v22
	v_rcp_f32_e32 v32, v22
	v_mul_f32_e32 v22, 0x3d372713, v31
	v_mul_f32_e32 v22, v31, v22
	v_fma_f32 v22, v31, v22, v31
	v_mul_f32_e32 v22, 0x3f4c422a, v22
	v_add_f32_e32 v22, v22, v22
	v_mul_f32_e32 v22, 0x3fb8aa3b, v22
	v_exp_f32_e32 v22, v22
	v_pk_mul_f32 v[30:31], v[30:31], 0.5 op_sel_hi:[1,0]
	v_add_f32_e32 v22, 1.0, v22
	v_rcp_f32_e32 v33, v22
	v_lshlrev_b32_e32 v22, 16, v23
	v_and_b32_e32 v23, 0xffff0000, v23
	v_pk_fma_f32 v[22:23], v[2:3], v[22:23], v[34:35]
	v_pk_fma_f32 v[32:33], v[32:33], 2.0, 1.0 op_sel_hi:[1,0,0] neg_lo:[1,0,0] neg_hi:[1,0,0]
	s_nop 0
	v_pk_add_f32 v[32:33], v[32:33], 1.0 op_sel_hi:[1,0]
	s_nop 0
	v_pk_mul_f32 v[30:31], v[30:31], v[32:33]
	v_mul_f32_e32 v32, 0x3d372713, v22
	v_mul_f32_e32 v33, 0x3d372713, v23
	v_mul_f32_e32 v32, v22, v32
	v_mul_f32_e32 v33, v23, v33
	v_fma_f32 v32, v22, v32, v22
	v_fma_f32 v33, v23, v33, v23
	v_mul_f32_e32 v32, 0x3f4c422a, v32
	v_mul_f32_e32 v33, 0x3f4c422a, v33
	v_add_f32_e32 v32, v32, v32
	v_add_f32_e32 v33, v33, v33
	v_mul_f32_e32 v32, 0x3fb8aa3b, v32
	v_mul_f32_e32 v33, 0x3fb8aa3b, v33
	v_exp_f32_e32 v32, v32
	v_exp_f32_e32 v33, v33
	v_pk_mul_f32 v[22:23], v[22:23], 0.5 op_sel_hi:[1,0]
	v_add_f32_e32 v32, 1.0, v32
	v_add_f32_e32 v33, 1.0, v33
	v_rcp_f32_e32 v32, v32
	v_rcp_f32_e32 v33, v33
	s_nop 0
	v_pk_fma_f32 v[32:33], v[32:33], 2.0, 1.0 op_sel_hi:[1,0,0] neg_lo:[1,0,0] neg_hi:[1,0,0]
	s_nop 0
	v_pk_add_f32 v[32:33], v[32:33], 1.0 op_sel_hi:[1,0]
	s_nop 0
	v_pk_mul_f32 v[32:33], v[22:23], v[32:33]
	v_cvt_pk_bf16_f32 v22, v30, v31
	v_or_b32_e32 v30, 0x4000, v20
	v_mov_b32_e32 v31, v21
	v_cvt_pk_bf16_f32 v23, v32, v33
	v_lshl_add_u64 v[30:31], v[24:25], 0, v[30:31]
	global_store_dwordx2 v[30:31], v[22:23], off
	s_waitcnt lgkmcnt(0)
	v_mov_b32_e32 v22, v124
; #define LAS __attribute__((address_space(3)))
; DI unsigned f2bf(float f) { unsigned u = __builtin_bit_cast(unsigned, f); return (u + 0x7fffu + ((u >> 16) & 1u)) >> 16; }
; DI void ssm_step_lds(const SsmC& c, const LAS bf16_t* up_, float& xr, float& xi) {
;     const LAS f32x4* up = (const LAS f32x4*)up_;
;     const f32x4 u0 = up[0], u1 = up[1], u2 = up[2], u3 = up[3];
;     float sr = 0.f, si = 0.f;
; #pragma unroll
;     for (int e = 0; e < 4; ++e) { sr += c.bbr[e] * u0[e]; si += c.bbi[e] * u0[e]; }
; #pragma unroll
;     for (int e = 0; e < 4; ++e) { sr += c.bbr[4 + e] * u1[e]; si += c.bbi[4 + e] * u1[e]; }
; #pragma unroll
;     for (int e = 0; e < 4; ++e) { sr += c.bbr[8 + e] * u2[e]; si += c.bbi[8 + e] * u2[e]; }
; #pragma unroll
;     for (int e = 0; e < 4; ++e) { sr += c.bbr[12 + e] * u3[e]; si += c.bbi[12 + e] * u3[e]; }
;     const float nxr = c.ar * xr - c.ai * xi + sr, nxi = c.ar * xi + c.ai * xr + si; xr = nxr; xi = nxi;
; }
; DI void ssm_s3(CArgs& a, int l, int it, int lane, LAS bf16_t* Xs  , LAS bf16_t* Us) {
;     ...
;         for (int tt = 0; tt < 32; ++tt) { ssm_step_lds(c, Us + (32 * sub + tt) * 32, xr, xi);
;             Xs[tt * 136 + lane] = (bf16_t)f2bf(xr); Xs[tt * 136 + 64 + lane] = (bf16_t)f2bf(xi); }
.LBB0_182:
	s_add_i32 s3, s0, s1
	s_add_i32 s4, s3, 0x12000
	v_mov_b32_e32 v23, s4
	ds_read_b128 v[30:33], v23
	s_add_i32 s4, s3, 0x12010
	v_mov_b32_e32 v23, s4
	ds_read_b128 v[34:37], v23
	s_add_i32 s4, s3, 0x12020
	s_waitcnt lgkmcnt(1)
	v_pk_fma_f32 v[48:49], v[74:75], v[30:31], 0 op_sel_hi:[1,0,0]
	v_mov_b32_e32 v23, s4
	v_pk_fma_f32 v[30:31], v[76:77], v[30:31], v[48:49] op_sel:[0,1,0]
	ds_read_b128 v[40:43], v23
	v_pk_fma_f32 v[30:31], v[78:79], v[32:33], v[30:31] op_sel_hi:[1,0,1]
	v_mov_b32_e32 v32, v33
	v_pk_fma_f32 v[30:31], v[98:99], v[32:33], v[30:31] op_sel_hi:[1,0,1]
	s_add_i32 s4, s3, 0x12030
	s_waitcnt lgkmcnt(1)
	v_pk_fma_f32 v[30:31], v[100:101], v[34:35], v[30:31] op_sel_hi:[1,0,1]
	v_mov_b32_e32 v23, s4
	v_pk_fma_f32 v[30:31], v[102:103], v[34:35], v[30:31] op_sel:[0,1,0]
	v_mov_b32_e32 v32, v37
	v_pk_fma_f32 v[30:31], v[104:105], v[36:37], v[30:31] op_sel_hi:[1,0,1]
	ds_read_b128 v[44:47], v23
	v_pk_fma_f32 v[30:31], v[106:107], v[32:33], v[30:31] op_sel_hi:[1,0,1]
	s_waitcnt lgkmcnt(1)
	v_mov_b32_e32 v34, v43
	v_pk_fma_f32 v[30:31], v[108:109], v[40:41], v[30:31] op_sel_hi:[1,0,1]
	v_pk_mul_f32 v[32:33], v[72:73], v[38:39]
	v_pk_fma_f32 v[30:31], v[110:111], v[40:41], v[30:31] op_sel:[0,1,0]
	s_add_i32 s4, s3, 0x12040
	v_pk_fma_f32 v[30:31], v[112:113], v[42:43], v[30:31] op_sel_hi:[1,0,1]
	s_addk_i32 s1, 0x100
	v_pk_fma_f32 v[30:31], v[114:115], v[34:35], v[30:31] op_sel_hi:[1,0,1]
	s_waitcnt lgkmcnt(0)
	v_mov_b32_e32 v34, v47
	v_pk_fma_f32 v[30:31], v[116:117], v[44:45], v[30:31] op_sel_hi:[1,0,1]
	s_nop 0
	v_pk_fma_f32 v[30:31], v[118:119], v[44:45], v[30:31] op_sel:[0,1,0]
	s_nop 0
	v_pk_fma_f32 v[30:31], v[120:121], v[46:47], v[30:31] op_sel_hi:[1,0,1]
	s_nop 0
	v_pk_fma_f32 v[30:31], v[122:123], v[34:35], v[30:31] op_sel_hi:[1,0,1]
	v_pk_fma_f32 v[34:35], v[70:71], v[38:39], v[32:33] op_sel:[0,0,1] op_sel_hi:[1,1,0]
	v_pk_fma_f32 v[32:33], v[70:71], v[38:39], v[32:33] op_sel:[0,0,1] op_sel_hi:[1,1,0] neg_lo:[0,0,1] neg_hi:[0,0,1]
	s_nop 0
	v_mov_b32_e32 v35, v33
	v_pk_add_f32 v[46:47], v[34:35], v[30:31]
	s_nop 0
	v_bfe_u32 v23, v47, 16, 1
	v_add3_u32 v23, v47, v23, s33
	ds_write_b16_d16_hi v22, v23
	v_bfe_u32 v23, v46, 16, 1
	v_add3_u32 v23, v46, v23, s33
	ds_write_b16_d16_hi v22, v23 offset:128
	v_mov_b32_e32 v23, s4
	ds_read_b128 v[30:33], v23
	s_add_i32 s4, s3, 0x12050
	v_mov_b32_e32 v23, s4
	ds_read_b128 v[34:37], v23
	s_add_i32 s4, s3, 0x12060
	s_waitcnt lgkmcnt(1)
	v_pk_fma_f32 v[48:49], v[74:75], v[30:31], 0 op_sel_hi:[1,0,0]
	v_mov_b32_e32 v23, s4
	v_pk_fma_f32 v[30:31], v[76:77], v[30:31], v[48:49] op_sel:[0,1,0]
	ds_read_b128 v[38:41], v23
	v_pk_fma_f32 v[30:31], v[78:79], v[32:33], v[30:31] op_sel_hi:[1,0,1]
	v_mov_b32_e32 v32, v33
	v_pk_fma_f32 v[30:31], v[98:99], v[32:33], v[30:31] op_sel_hi:[1,0,1]
	s_add_i32 s4, s3, 0x12070
	s_waitcnt lgkmcnt(1)
	v_pk_fma_f32 v[30:31], v[100:101], v[34:35], v[30:31] op_sel_hi:[1,0,1]
	v_mov_b32_e32 v23, s4
	v_pk_fma_f32 v[30:31], v[102:103], v[34:35], v[30:31] op_sel:[0,1,0]
	v_mov_b32_e32 v32, v37
	v_pk_fma_f32 v[30:31], v[104:105], v[36:37], v[30:31] op_sel_hi:[1,0,1]
	ds_read_b128 v[42:45], v23
	v_pk_fma_f32 v[30:31], v[106:107], v[32:33], v[30:31] op_sel_hi:[1,0,1]
	s_waitcnt lgkmcnt(1)
	v_mov_b32_e32 v34, v41
	v_pk_fma_f32 v[30:31], v[108:109], v[38:39], v[30:31] op_sel_hi:[1,0,1]
	v_pk_mul_f32 v[32:33], v[72:73], v[46:47]
	v_pk_fma_f32 v[30:31], v[110:111], v[38:39], v[30:31] op_sel:[0,1,0]
	s_add_i32 s4, s3, 0x12080
	v_pk_fma_f32 v[30:31], v[112:113], v[40:41], v[30:31] op_sel_hi:[1,0,1]
	s_nop 0
	v_pk_fma_f32 v[30:31], v[114:115], v[34:35], v[30:31] op_sel_hi:[1,0,1]
	s_waitcnt lgkmcnt(0)
	v_mov_b32_e32 v34, v45
	v_pk_fma_f32 v[30:31], v[116:117], v[42:43], v[30:31] op_sel_hi:[1,0,1]
	s_nop 0
	v_pk_fma_f32 v[30:31], v[118:119], v[42:43], v[30:31] op_sel:[0,1,0]
	s_nop 0
	v_pk_fma_f32 v[30:31], v[120:121], v[44:45], v[30:31] op_sel_hi:[1,0,1]
	s_nop 0
	v_pk_fma_f32 v[30:31], v[122:123], v[34:35], v[30:31] op_sel_hi:[1,0,1]
	v_pk_fma_f32 v[34:35], v[70:71], v[46:47], v[32:33] op_sel:[0,0,1] op_sel_hi:[1,1,0]
	v_pk_fma_f32 v[32:33], v[70:71], v[46:47], v[32:33] op_sel:[0,0,1] op_sel_hi:[1,1,0] neg_lo:[0,0,1] neg_hi:[0,0,1]
	s_nop 0
	v_mov_b32_e32 v35, v33
	v_pk_add_f32 v[46:47], v[34:35], v[30:31]
	s_nop 0
	v_bfe_u32 v23, v47, 16, 1
	v_add3_u32 v23, v47, v23, s33
	ds_write_b16_d16_hi v22, v23 offset:272
	v_bfe_u32 v23, v46, 16, 1
	v_add3_u32 v23, v46, v23, s33
	ds_write_b16_d16_hi v22, v23 offset:400
	v_mov_b32_e32 v23, s4
	ds_read_b128 v[30:33], v23
	s_add_i32 s4, s3, 0x12090
	v_mov_b32_e32 v23, s4
	ds_read_b128 v[34:37], v23
	s_add_i32 s4, s3, 0x120a0
	s_waitcnt lgkmcnt(1)
	v_pk_fma_f32 v[48:49], v[74:75], v[30:31], 0 op_sel_hi:[1,0,0]
	v_mov_b32_e32 v23, s4
	v_pk_fma_f32 v[30:31], v[76:77], v[30:31], v[48:49] op_sel:[0,1,0]
	ds_read_b128 v[38:41], v23
	v_pk_fma_f32 v[30:31], v[78:79], v[32:33], v[30:31] op_sel_hi:[1,0,1]
	v_mov_b32_e32 v32, v33
	v_pk_fma_f32 v[30:31], v[98:99], v[32:33], v[30:31] op_sel_hi:[1,0,1]
	s_add_i32 s4, s3, 0x120b0
	s_waitcnt lgkmcnt(1)
	v_pk_fma_f32 v[30:31], v[100:101], v[34:35], v[30:31] op_sel_hi:[1,0,1]
	v_mov_b32_e32 v23, s4
	v_pk_fma_f32 v[30:31], v[102:103], v[34:35], v[30:31] op_sel:[0,1,0]
	v_mov_b32_e32 v32, v37
	v_pk_fma_f32 v[30:31], v[104:105], v[36:37], v[30:31] op_sel_hi:[1,0,1]
	ds_read_b128 v[42:45], v23
	v_pk_fma_f32 v[30:31], v[106:107], v[32:33], v[30:31] op_sel_hi:[1,0,1]
	s_waitcnt lgkmcnt(1)
	v_mov_b32_e32 v34, v41
	v_pk_fma_f32 v[30:31], v[108:109], v[38:39], v[30:31] op_sel_hi:[1,0,1]
	v_pk_mul_f32 v[32:33], v[72:73], v[46:47]
	v_pk_fma_f32 v[30:31], v[110:111], v[38:39], v[30:31] op_sel:[0,1,0]
	s_add_i32 s4, s3, 0x120c0
	v_pk_fma_f32 v[30:31], v[112:113], v[40:41], v[30:31] op_sel_hi:[1,0,1]
	s_nop 0
	v_pk_fma_f32 v[30:31], v[114:115], v[34:35], v[30:31] op_sel_hi:[1,0,1]
	s_waitcnt lgkmcnt(0)
; DI unsigned f2bf(float f) { unsigned u = __builtin_bit_cast(unsigned, f); return (u + 0x7fffu + ((u >> 16) & 1u)) >> 16; }
; DI unsigned pk2(float lo, float hi) { f32x2 v = {lo, hi}; bf16x2_t b = __builtin_convertvector(v, bf16x2_t); return __builtin_bit_cast(unsigned, b); }
; DI float bflo(unsigned w) { return __uint_as_float(w << 16); }
; DI float bfhi(unsigned w) { return __uint_as_float(w & 0xffff0000u); }
; DI float geluf_(float x) { const float a = 0.7978845608028654f * (x + 0.044715f * x * x * x); const float t = 1.f - 2.f * __builtin_amdgcn_rcpf(__expf(2.f * a) + 1.f); return 0.5f * x * (1.f + t); }
; #define MFMA16(a, b, c) __builtin_amdgcn_mfma_f32_16x16x32_bf16((a), (b), (c), 0, 0, 0)
; DI void ssm_s3(CArgs& a, int l, int it, int lane, LAS bf16_t* Xs  , LAS bf16_t* Us) {
;     ...
;         for (int tt = 0; tt < 32; ++tt) { ssm_step_lds(c, Us + (32 * sub + tt) * 32, xr, xi);
;             Xs[tt * 136 + lane] = (bf16_t)f2bf(xr); Xs[tt * 136 + 64 + lane] = (bf16_t)f2bf(xi); }
;         asm volatile("s_waitcnt lgkmcnt(0)" ::: "memory");
; #pragma unroll
;         for (int m = 0; m < 2; ++m) {
;             float zz = 0.f; asm volatile("" : "+v"(zz)); f32x4 acc = {zz, zz, zz, zz};
; #pragma unroll
;             for (int kk = 0; kk < 4; ++kk) { const bf16x8 xf = lds_b128(Xs + (16 * m + fr) * 136 + 32 * kk + 8 * fq); acc = MFMA16(cf[kk], xf, acc); }
;             const size_t tg = t0 + 32 * sub + 16 * m + fr;
;             const u32x2 uw = *(const u32x2*)(zb + tg * NZ + ZU + g * 16 + 4 * fq);
;             const float y0 = geluf_(acc[0] + dsk[0] * bflo(uw.x)), y1 = geluf_(acc[1] + dsk[1] * bfhi(uw.x)), y2 = geluf_(acc[2] + dsk[2] * bflo(uw.y)), y3 = geluf_(acc[3] + dsk[3] * bfhi(uw.y));
;             u32x2 ow; ow.x = pk2(y0, y1); ow.y = pk2(y2, y3);
;             *(u32x2*)(gb + tg * 512 + g * 16 + 4 * fq) = ow;
	v_mov_b32_e32 v34, v45
	v_pk_fma_f32 v[30:31], v[116:117], v[42:43], v[30:31] op_sel_hi:[1,0,1]
	s_nop 0
	v_pk_fma_f32 v[30:31], v[118:119], v[42:43], v[30:31] op_sel:[0,1,0]
	s_nop 0
	v_pk_fma_f32 v[30:31], v[120:121], v[44:45], v[30:31] op_sel_hi:[1,0,1]
	s_nop 0
	v_pk_fma_f32 v[30:31], v[122:123], v[34:35], v[30:31] op_sel_hi:[1,0,1]
	v_pk_fma_f32 v[34:35], v[70:71], v[46:47], v[32:33] op_sel:[0,0,1] op_sel_hi:[1,1,0]
	v_pk_fma_f32 v[32:33], v[70:71], v[46:47], v[32:33] op_sel:[0,0,1] op_sel_hi:[1,1,0] neg_lo:[0,0,1] neg_hi:[0,0,1]
	s_nop 0
	v_mov_b32_e32 v35, v33
	v_pk_add_f32 v[46:47], v[34:35], v[30:31]
	s_nop 0
	v_bfe_u32 v23, v47, 16, 1
	v_add3_u32 v23, v47, v23, s33
	ds_write_b16_d16_hi v22, v23 offset:544
	v_bfe_u32 v23, v46, 16, 1
	v_add3_u32 v23, v46, v23, s33
	ds_write_b16_d16_hi v22, v23 offset:672
	v_mov_b32_e32 v23, s4
	ds_read_b128 v[30:33], v23
	s_add_i32 s4, s3, 0x120d0
	v_mov_b32_e32 v23, s4
	ds_read_b128 v[34:37], v23
	s_add_i32 s4, s3, 0x120e0
	s_waitcnt lgkmcnt(1)
	v_pk_fma_f32 v[48:49], v[74:75], v[30:31], 0 op_sel_hi:[1,0,0]
	v_mov_b32_e32 v23, s4
	v_pk_fma_f32 v[30:31], v[76:77], v[30:31], v[48:49] op_sel:[0,1,0]
	ds_read_b128 v[38:41], v23
	v_pk_fma_f32 v[30:31], v[78:79], v[32:33], v[30:31] op_sel_hi:[1,0,1]
	v_mov_b32_e32 v32, v33
	v_pk_fma_f32 v[30:31], v[98:99], v[32:33], v[30:31] op_sel_hi:[1,0,1]
	s_add_i32 s3, s3, 0x120f0
	s_waitcnt lgkmcnt(1)
	v_pk_fma_f32 v[30:31], v[100:101], v[34:35], v[30:31] op_sel_hi:[1,0,1]
	v_mov_b32_e32 v23, s3
	v_pk_fma_f32 v[30:31], v[102:103], v[34:35], v[30:31] op_sel:[0,1,0]
	v_mov_b32_e32 v32, v37
	v_pk_fma_f32 v[30:31], v[104:105], v[36:37], v[30:31] op_sel_hi:[1,0,1]
	ds_read_b128 v[42:45], v23
	v_pk_fma_f32 v[30:31], v[106:107], v[32:33], v[30:31] op_sel_hi:[1,0,1]
	s_waitcnt lgkmcnt(1)
	v_mov_b32_e32 v34, v41
	v_pk_fma_f32 v[30:31], v[108:109], v[38:39], v[30:31] op_sel_hi:[1,0,1]
	v_pk_mul_f32 v[32:33], v[72:73], v[46:47]
	v_pk_fma_f32 v[30:31], v[110:111], v[38:39], v[30:31] op_sel:[0,1,0]
	s_cmp_lg_u32 s1, 0
	v_pk_fma_f32 v[30:31], v[112:113], v[40:41], v[30:31] op_sel_hi:[1,0,1]
	s_nop 0
	v_pk_fma_f32 v[30:31], v[114:115], v[34:35], v[30:31] op_sel_hi:[1,0,1]
	s_waitcnt lgkmcnt(0)
	v_mov_b32_e32 v34, v45
	v_pk_fma_f32 v[30:31], v[116:117], v[42:43], v[30:31] op_sel_hi:[1,0,1]
	s_nop 0
	v_pk_fma_f32 v[30:31], v[118:119], v[42:43], v[30:31] op_sel:[0,1,0]
	s_nop 0
	v_pk_fma_f32 v[30:31], v[120:121], v[44:45], v[30:31] op_sel_hi:[1,0,1]
	s_nop 0
	v_pk_fma_f32 v[30:31], v[122:123], v[34:35], v[30:31] op_sel_hi:[1,0,1]
	v_pk_fma_f32 v[34:35], v[70:71], v[46:47], v[32:33] op_sel:[0,0,1] op_sel_hi:[1,1,0]
	v_pk_fma_f32 v[32:33], v[70:71], v[46:47], v[32:33] op_sel:[0,0,1] op_sel_hi:[1,1,0] neg_lo:[0,0,1] neg_hi:[0,0,1]
	s_nop 0
	v_mov_b32_e32 v35, v33
	v_pk_add_f32 v[38:39], v[34:35], v[30:31]
	s_nop 0
	v_bfe_u32 v23, v39, 16, 1
	v_add3_u32 v23, v39, v23, s33
	ds_write_b16_d16_hi v22, v23 offset:816
	v_bfe_u32 v23, v38, 16, 1
	v_add3_u32 v23, v38, v23, s33
	ds_write_b16_d16_hi v22, v23 offset:944
	v_add_u32_e32 v22, 0x440, v22
	s_cbranch_scc1 .LBB0_182
	v_mov_b32_e32 v30, v81
	s_waitcnt lgkmcnt(0)
	ds_read_b128 v[34:37], v126
	v_mov_b32_e32 v31, v30
	v_mov_b32_e32 v32, v30
	v_mov_b32_e32 v33, v30
	v_or_b32_e32 v40, 32, v26
	v_mad_u64_u32 v[22:23], s[4:5], v40, s55, v[28:29]
	s_waitcnt lgkmcnt(0)
	v_mfma_f32_16x16x32_bf16 v[30:33], v[4:7], v[34:37], v[30:33]
	ds_read_b128 v[34:37], v126 offset:64
	v_mad_i32_i24 v23, v27, s55, v23
	v_mov_b32_e32 v41, v27
	s_waitcnt lgkmcnt(0)
	v_mfma_f32_16x16x32_bf16 v[30:33], v[8:11], v[34:37], v[30:33]
	ds_read_b128 v[34:37], v126 offset:128
	s_movk_i32 s1, 0xf800
	s_waitcnt lgkmcnt(0)
	v_mfma_f32_16x16x32_bf16 v[30:33], v[12:15], v[34:37], v[30:33]
	ds_read_b128 v[34:37], v126 offset:192
	s_waitcnt lgkmcnt(0)
	v_mfma_f32_16x16x32_bf16 v[30:33], v[16:19], v[34:37], v[30:33]
	v_add_co_u32_e32 v22, vcc, s79, v22
	s_waitcnt vmcnt(5)
	v_mov_b32_e32 v34, v236
	v_mov_b32_e32 v35, v237
	v_lshlrev_b32_e32 v36, 16, v34
	v_and_b32_e32 v37, 0xffff0000, v34
	s_nop 2
	v_pk_fma_f32 v[30:31], v[0:1], v[36:37], v[30:31]
	v_addc_co_u32_e32 v23, vcc, 0, v23, vcc
	v_mul_f32_e32 v34, 0x3d372713, v30
	v_mul_f32_e32 v34, v30, v34
	v_fma_f32 v34, v30, v34, v30
	v_mul_f32_e32 v34, 0x3f4c422a, v34
	v_add_f32_e32 v34, v34, v34
	v_mul_f32_e32 v34, 0x3fb8aa3b, v34
	v_exp_f32_e32 v34, v34
	s_nop 0
	v_add_f32_e32 v34, 1.0, v34
	v_rcp_f32_e32 v36, v34
	v_mul_f32_e32 v34, 0x3d372713, v31
	v_mul_f32_e32 v34, v31, v34
	v_fma_f32 v34, v31, v34, v31
	v_mul_f32_e32 v34, 0x3f4c422a, v34
	v_add_f32_e32 v34, v34, v34
	v_mul_f32_e32 v34, 0x3fb8aa3b, v34
	v_exp_f32_e32 v34, v34
	v_pk_mul_f32 v[30:31], v[30:31], 0.5 op_sel_hi:[1,0]
	v_add_f32_e32 v34, 1.0, v34
	v_rcp_f32_e32 v37, v34
	v_lshlrev_b32_e32 v34, 16, v35
	v_and_b32_e32 v35, 0xffff0000, v35
	v_pk_fma_f32 v[32:33], v[2:3], v[34:35], v[32:33]
	v_pk_fma_f32 v[36:37], v[36:37], 2.0, 1.0 op_sel_hi:[1,0,0] neg_lo:[1,0,0] neg_hi:[1,0,0]
	v_mul_f32_e32 v34, 0x3d372713, v32
	v_mul_f32_e32 v35, 0x3d372713, v33
	v_mul_f32_e32 v34, v32, v34
	v_mul_f32_e32 v35, v33, v35
	v_fma_f32 v34, v32, v34, v32
	v_fma_f32 v35, v33, v35, v33
	v_mul_f32_e32 v34, 0x3f4c422a, v34
	v_mul_f32_e32 v35, 0x3f4c422a, v35
	v_add_f32_e32 v34, v34, v34
	v_add_f32_e32 v35, v35, v35
	v_mul_f32_e32 v34, 0x3fb8aa3b, v34
	v_mul_f32_e32 v35, 0x3fb8aa3b, v35
	v_exp_f32_e32 v34, v34
	v_exp_f32_e32 v35, v35
	v_pk_add_f32 v[36:37], v[36:37], 1.0 op_sel_hi:[1,0]
	v_pk_mul_f32 v[32:33], v[32:33], 0.5 op_sel_hi:[1,0]
	v_add_f32_e32 v34, 1.0, v34
	v_add_f32_e32 v35, 1.0, v35
	v_rcp_f32_e32 v34, v34
	v_rcp_f32_e32 v35, v35
	v_pk_mul_f32 v[30:31], v[30:31], v[36:37]
	v_pk_fma_f32 v[34:35], v[34:35], 2.0, 1.0 op_sel_hi:[1,0,0] neg_lo:[1,0,0] neg_hi:[1,0,0]
	s_nop 0
	v_pk_add_f32 v[34:35], v[34:35], 1.0 op_sel_hi:[1,0]
	v_cvt_pk_bf16_f32 v30, v30, v31
	v_pk_mul_f32 v[32:33], v[32:33], v[34:35]
	s_nop 0
	v_cvt_pk_bf16_f32 v31, v32, v33
	v_lshlrev_b64 v[32:33], 10, v[40:41]
	v_lshl_add_u64 v[32:33], v[24:25], 0, v[32:33]
	global_store_dwordx2 v[32:33], v[30:31], off
	v_mov_b32_e32 v30, v81
	ds_read_b128 v[34:37], v126 offset:4352
	v_mov_b32_e32 v31, v30
	v_mov_b32_e32 v32, v30
	v_mov_b32_e32 v33, v30
	s_waitcnt lgkmcnt(0)
; DI unsigned f2bf(float f) { unsigned u = __builtin_bit_cast(unsigned, f); return (u + 0x7fffu + ((u >> 16) & 1u)) >> 16; }
; DI unsigned pk2(float lo, float hi) { f32x2 v = {lo, hi}; bf16x2_t b = __builtin_convertvector(v, bf16x2_t); return __builtin_bit_cast(unsigned, b); }
; DI float bflo(unsigned w) { return __uint_as_float(w << 16); }
; DI float bfhi(unsigned w) { return __uint_as_float(w & 0xffff0000u); }
; DI float geluf_(float x) { const float a = 0.7978845608028654f * (x + 0.044715f * x * x * x); const float t = 1.f - 2.f * __builtin_amdgcn_rcpf(__expf(2.f * a) + 1.f); return 0.5f * x * (1.f + t); }
; #define MFMA16(a, b, c) __builtin_amdgcn_mfma_f32_16x16x32_bf16((a), (b), (c), 0, 0, 0)
; DI void ssm_s3(CArgs& a, int l, int it, int lane, LAS bf16_t* Xs  , LAS bf16_t* Us) {
;     ...
;         for (int tt = 0; tt < 32; ++tt) { ssm_step_lds(c, Us + (32 * sub + tt) * 32, xr, xi);
;             Xs[tt * 136 + lane] = (bf16_t)f2bf(xr); Xs[tt * 136 + 64 + lane] = (bf16_t)f2bf(xi); }
;     ...
;         for (int m = 0; m < 2; ++m) {
;             float zz = 0.f; asm volatile("" : "+v"(zz)); f32x4 acc = {zz, zz, zz, zz};
; #pragma unroll
;             for (int kk = 0; kk < 4; ++kk) { const bf16x8 xf = lds_b128(Xs + (16 * m + fr) * 136 + 32 * kk + 8 * fq); acc = MFMA16(cf[kk], xf, acc); }
;             const size_t tg = t0 + 32 * sub + 16 * m + fr;
;             const u32x2 uw = *(const u32x2*)(zb + tg * NZ + ZU + g * 16 + 4 * fq);
;             const float y0 = geluf_(acc[0] + dsk[0] * bflo(uw.x)), y1 = geluf_(acc[1] + dsk[1] * bfhi(uw.x)), y2 = geluf_(acc[2] + dsk[2] * bflo(uw.y)), y3 = geluf_(acc[3] + dsk[3] * bfhi(uw.y));
;             u32x2 ow; ow.x = pk2(y0, y1); ow.y = pk2(y2, y3);
;             *(u32x2*)(gb + tg * 512 + g * 16 + 4 * fq) = ow;
	s_nop 0
	v_mfma_f32_16x16x32_bf16 v[30:33], v[4:7], v[34:37], v[30:33]
	ds_read_b128 v[34:37], v126 offset:4416
	s_waitcnt lgkmcnt(0)
	v_mfma_f32_16x16x32_bf16 v[30:33], v[8:11], v[34:37], v[30:33]
	ds_read_b128 v[34:37], v126 offset:4480
	s_waitcnt lgkmcnt(0)
	v_mfma_f32_16x16x32_bf16 v[30:33], v[12:15], v[34:37], v[30:33]
	ds_read_b128 v[34:37], v126 offset:4544
	s_waitcnt lgkmcnt(0)
	v_mfma_f32_16x16x32_bf16 v[30:33], v[16:19], v[34:37], v[30:33]
	s_waitcnt vmcnt(4)
	v_mov_b32_e32 v22, v238
	v_mov_b32_e32 v23, v239
	v_lshlrev_b32_e32 v34, 16, v22
	v_and_b32_e32 v35, 0xffff0000, v22
	s_nop 4
	v_pk_fma_f32 v[30:31], v[0:1], v[34:35], v[30:31]
	s_nop 0
	v_mul_f32_e32 v22, 0x3d372713, v30
	v_mul_f32_e32 v22, v30, v22
	v_fma_f32 v22, v30, v22, v30
	v_mul_f32_e32 v22, 0x3f4c422a, v22
	v_add_f32_e32 v22, v22, v22
	v_mul_f32_e32 v22, 0x3fb8aa3b, v22
	v_exp_f32_e32 v22, v22
	s_nop 0
	v_add_f32_e32 v22, 1.0, v22
	v_rcp_f32_e32 v34, v22
	v_mul_f32_e32 v22, 0x3d372713, v31
	v_mul_f32_e32 v22, v31, v22
	v_fma_f32 v22, v31, v22, v31
	v_mul_f32_e32 v22, 0x3f4c422a, v22
	v_add_f32_e32 v22, v22, v22
	v_mul_f32_e32 v22, 0x3fb8aa3b, v22
	v_exp_f32_e32 v22, v22
	v_pk_mul_f32 v[30:31], v[30:31], 0.5 op_sel_hi:[1,0]
	v_add_f32_e32 v22, 1.0, v22
	v_rcp_f32_e32 v35, v22
	v_lshlrev_b32_e32 v22, 16, v23
	v_and_b32_e32 v23, 0xffff0000, v23
	v_pk_fma_f32 v[22:23], v[2:3], v[22:23], v[32:33]
	v_pk_fma_f32 v[34:35], v[34:35], 2.0, 1.0 op_sel_hi:[1,0,0] neg_lo:[1,0,0] neg_hi:[1,0,0]
	v_mul_f32_e32 v32, 0x3d372713, v22
	v_mul_f32_e32 v33, 0x3d372713, v23
	v_mul_f32_e32 v32, v22, v32
	v_mul_f32_e32 v33, v23, v33
	v_fma_f32 v32, v22, v32, v22
	v_fma_f32 v33, v23, v33, v23
	v_mul_f32_e32 v32, 0x3f4c422a, v32
	v_mul_f32_e32 v33, 0x3f4c422a, v33
	v_add_f32_e32 v32, v32, v32
	v_add_f32_e32 v33, v33, v33
	v_mul_f32_e32 v32, 0x3fb8aa3b, v32
	v_mul_f32_e32 v33, 0x3fb8aa3b, v33
	v_exp_f32_e32 v32, v32
	v_exp_f32_e32 v33, v33
	v_pk_add_f32 v[34:35], v[34:35], 1.0 op_sel_hi:[1,0]
	v_pk_mul_f32 v[22:23], v[22:23], 0.5 op_sel_hi:[1,0]
	v_add_f32_e32 v32, 1.0, v32
	v_add_f32_e32 v33, 1.0, v33
	v_rcp_f32_e32 v32, v32
	v_rcp_f32_e32 v33, v33
	v_pk_mul_f32 v[30:31], v[30:31], v[34:35]
	v_pk_fma_f32 v[32:33], v[32:33], 2.0, 1.0 op_sel_hi:[1,0,0] neg_lo:[1,0,0] neg_hi:[1,0,0]
	s_nop 0
	v_pk_add_f32 v[32:33], v[32:33], 1.0 op_sel_hi:[1,0]
	s_nop 0
	v_pk_mul_f32 v[32:33], v[22:23], v[32:33]
	v_cvt_pk_bf16_f32 v22, v30, v31
	v_or_b32_e32 v30, 0xc000, v20
	v_mov_b32_e32 v31, v21
	v_cvt_pk_bf16_f32 v23, v32, v33
	v_lshl_add_u64 v[30:31], v[24:25], 0, v[30:31]
	global_store_dwordx2 v[30:31], v[22:23], off
	s_waitcnt lgkmcnt(0)
	v_mov_b32_e32 v22, v124
.LBB0_184:
	s_add_i32 s3, s0, s1
	s_add_i32 s4, s3, 0x12800
	v_mov_b32_e32 v23, s4
	ds_read_b128 v[30:33], v23
	s_add_i32 s4, s3, 0x12810
	v_mov_b32_e32 v23, s4
	ds_read_b128 v[34:37], v23
	s_add_i32 s4, s3, 0x12820
	s_waitcnt lgkmcnt(1)
	v_pk_fma_f32 v[48:49], v[74:75], v[30:31], 0 op_sel_hi:[1,0,0]
	v_mov_b32_e32 v23, s4
	v_pk_fma_f32 v[30:31], v[76:77], v[30:31], v[48:49] op_sel:[0,1,0]
	ds_read_b128 v[40:43], v23
	v_pk_fma_f32 v[30:31], v[78:79], v[32:33], v[30:31] op_sel_hi:[1,0,1]
	v_mov_b32_e32 v32, v33
	v_pk_fma_f32 v[30:31], v[98:99], v[32:33], v[30:31] op_sel_hi:[1,0,1]
	s_add_i32 s4, s3, 0x12830
	s_waitcnt lgkmcnt(1)
	v_pk_fma_f32 v[30:31], v[100:101], v[34:35], v[30:31] op_sel_hi:[1,0,1]
	v_mov_b32_e32 v23, s4
	v_pk_fma_f32 v[30:31], v[102:103], v[34:35], v[30:31] op_sel:[0,1,0]
	v_mov_b32_e32 v34, v37
	v_pk_fma_f32 v[30:31], v[104:105], v[36:37], v[30:31] op_sel_hi:[1,0,1]
	ds_read_b128 v[44:47], v23
	v_pk_fma_f32 v[30:31], v[106:107], v[34:35], v[30:31] op_sel_hi:[1,0,1]
	s_waitcnt lgkmcnt(1)
	v_mov_b32_e32 v34, v43
	v_pk_fma_f32 v[30:31], v[108:109], v[40:41], v[30:31] op_sel_hi:[1,0,1]
	v_pk_mul_f32 v[32:33], v[72:73], v[38:39]
	v_pk_fma_f32 v[30:31], v[110:111], v[40:41], v[30:31] op_sel:[0,1,0]
	s_add_i32 s4, s3, 0x12840
	v_pk_fma_f32 v[30:31], v[112:113], v[42:43], v[30:31] op_sel_hi:[1,0,1]
	s_addk_i32 s1, 0x100
	v_pk_fma_f32 v[30:31], v[114:115], v[34:35], v[30:31] op_sel_hi:[1,0,1]
	s_waitcnt lgkmcnt(0)
	v_mov_b32_e32 v34, v47
	v_pk_fma_f32 v[30:31], v[116:117], v[44:45], v[30:31] op_sel_hi:[1,0,1]
	s_nop 0
	v_pk_fma_f32 v[30:31], v[118:119], v[44:45], v[30:31] op_sel:[0,1,0]
	s_nop 0
	v_pk_fma_f32 v[30:31], v[120:121], v[46:47], v[30:31] op_sel_hi:[1,0,1]
	s_nop 0
	v_pk_fma_f32 v[30:31], v[122:123], v[34:35], v[30:31] op_sel_hi:[1,0,1]
	v_pk_fma_f32 v[34:35], v[70:71], v[38:39], v[32:33] op_sel:[0,0,1] op_sel_hi:[1,1,0]
	v_pk_fma_f32 v[32:33], v[70:71], v[38:39], v[32:33] op_sel:[0,0,1] op_sel_hi:[1,1,0] neg_lo:[0,0,1] neg_hi:[0,0,1]
	s_nop 0
	v_mov_b32_e32 v35, v33
	v_pk_add_f32 v[46:47], v[34:35], v[30:31]
	s_nop 0
	v_bfe_u32 v23, v47, 16, 1
	v_add3_u32 v23, v47, v23, s33
	ds_write_b16_d16_hi v22, v23
	v_bfe_u32 v23, v46, 16, 1
	v_add3_u32 v23, v46, v23, s33
	ds_write_b16_d16_hi v22, v23 offset:128
	v_mov_b32_e32 v23, s4
	ds_read_b128 v[30:33], v23
	s_add_i32 s4, s3, 0x12850
	v_mov_b32_e32 v23, s4
	ds_read_b128 v[34:37], v23
	s_add_i32 s4, s3, 0x12860
	s_waitcnt lgkmcnt(1)
	v_pk_fma_f32 v[48:49], v[74:75], v[30:31], 0 op_sel_hi:[1,0,0]
	v_mov_b32_e32 v23, s4
	v_pk_fma_f32 v[30:31], v[76:77], v[30:31], v[48:49] op_sel:[0,1,0]
	ds_read_b128 v[38:41], v23
	v_pk_fma_f32 v[30:31], v[78:79], v[32:33], v[30:31] op_sel_hi:[1,0,1]
	v_mov_b32_e32 v32, v33
	v_pk_fma_f32 v[30:31], v[98:99], v[32:33], v[30:31] op_sel_hi:[1,0,1]
	s_add_i32 s4, s3, 0x12870
	s_waitcnt lgkmcnt(1)
; #define LAS __attribute__((address_space(3)))
; DI unsigned f2bf(float f) { unsigned u = __builtin_bit_cast(unsigned, f); return (u + 0x7fffu + ((u >> 16) & 1u)) >> 16; }
; DI void ssm_step_lds(const SsmC& c, const LAS bf16_t* up_, float& xr, float& xi) {
;     const LAS f32x4* up = (const LAS f32x4*)up_;
;     const f32x4 u0 = up[0], u1 = up[1], u2 = up[2], u3 = up[3];
;     float sr = 0.f, si = 0.f;
; #pragma unroll
;     for (int e = 0; e < 4; ++e) { sr += c.bbr[e] * u0[e]; si += c.bbi[e] * u0[e]; }
; #pragma unroll
;     for (int e = 0; e < 4; ++e) { sr += c.bbr[4 + e] * u1[e]; si += c.bbi[4 + e] * u1[e]; }
; #pragma unroll
;     for (int e = 0; e < 4; ++e) { sr += c.bbr[8 + e] * u2[e]; si += c.bbi[8 + e] * u2[e]; }
; #pragma unroll
;     for (int e = 0; e < 4; ++e) { sr += c.bbr[12 + e] * u3[e]; si += c.bbi[12 + e] * u3[e]; }
;     const float nxr = c.ar * xr - c.ai * xi + sr, nxi = c.ar * xi + c.ai * xr + si; xr = nxr; xi = nxi;
; }
; DI void ssm_s3(CArgs& a, int l, int it, int lane, LAS bf16_t* Xs  , LAS bf16_t* Us) {
;     ...
;         for (int tt = 0; tt < 32; ++tt) { ssm_step_lds(c, Us + (32 * sub + tt) * 32, xr, xi);
;             Xs[tt * 136 + lane] = (bf16_t)f2bf(xr); Xs[tt * 136 + 64 + lane] = (bf16_t)f2bf(xi); }
	v_pk_fma_f32 v[30:31], v[100:101], v[34:35], v[30:31] op_sel_hi:[1,0,1]
	v_mov_b32_e32 v23, s4
	v_pk_fma_f32 v[30:31], v[102:103], v[34:35], v[30:31] op_sel:[0,1,0]
	v_mov_b32_e32 v34, v37
	v_pk_fma_f32 v[30:31], v[104:105], v[36:37], v[30:31] op_sel_hi:[1,0,1]
	ds_read_b128 v[42:45], v23
	v_pk_fma_f32 v[30:31], v[106:107], v[34:35], v[30:31] op_sel_hi:[1,0,1]
	s_waitcnt lgkmcnt(1)
	v_mov_b32_e32 v34, v41
	v_pk_fma_f32 v[30:31], v[108:109], v[38:39], v[30:31] op_sel_hi:[1,0,1]
	v_pk_mul_f32 v[32:33], v[72:73], v[46:47]
	v_pk_fma_f32 v[30:31], v[110:111], v[38:39], v[30:31] op_sel:[0,1,0]
	s_add_i32 s4, s3, 0x12880
	v_pk_fma_f32 v[30:31], v[112:113], v[40:41], v[30:31] op_sel_hi:[1,0,1]
	s_nop 0
	v_pk_fma_f32 v[30:31], v[114:115], v[34:35], v[30:31] op_sel_hi:[1,0,1]
	s_waitcnt lgkmcnt(0)
	v_mov_b32_e32 v34, v45
	v_pk_fma_f32 v[30:31], v[116:117], v[42:43], v[30:31] op_sel_hi:[1,0,1]
	s_nop 0
	v_pk_fma_f32 v[30:31], v[118:119], v[42:43], v[30:31] op_sel:[0,1,0]
	s_nop 0
	v_pk_fma_f32 v[30:31], v[120:121], v[44:45], v[30:31] op_sel_hi:[1,0,1]
	s_nop 0
	v_pk_fma_f32 v[30:31], v[122:123], v[34:35], v[30:31] op_sel_hi:[1,0,1]
	v_pk_fma_f32 v[34:35], v[70:71], v[46:47], v[32:33] op_sel:[0,0,1] op_sel_hi:[1,1,0]
	v_pk_fma_f32 v[32:33], v[70:71], v[46:47], v[32:33] op_sel:[0,0,1] op_sel_hi:[1,1,0] neg_lo:[0,0,1] neg_hi:[0,0,1]
	s_nop 0
	v_mov_b32_e32 v35, v33
	v_pk_add_f32 v[46:47], v[34:35], v[30:31]
	s_nop 0
	v_bfe_u32 v23, v47, 16, 1
	v_add3_u32 v23, v47, v23, s33
	ds_write_b16_d16_hi v22, v23 offset:272
	v_bfe_u32 v23, v46, 16, 1
	v_add3_u32 v23, v46, v23, s33
	ds_write_b16_d16_hi v22, v23 offset:400
	v_mov_b32_e32 v23, s4
	ds_read_b128 v[30:33], v23
	s_add_i32 s4, s3, 0x12890
	v_mov_b32_e32 v23, s4
	ds_read_b128 v[34:37], v23
	s_add_i32 s4, s3, 0x128a0
	s_waitcnt lgkmcnt(1)
	v_pk_fma_f32 v[48:49], v[74:75], v[30:31], 0 op_sel_hi:[1,0,0]
	v_mov_b32_e32 v23, s4
	v_pk_fma_f32 v[30:31], v[76:77], v[30:31], v[48:49] op_sel:[0,1,0]
	ds_read_b128 v[38:41], v23
	v_pk_fma_f32 v[30:31], v[78:79], v[32:33], v[30:31] op_sel_hi:[1,0,1]
	v_mov_b32_e32 v32, v33
	v_pk_fma_f32 v[30:31], v[98:99], v[32:33], v[30:31] op_sel_hi:[1,0,1]
	s_add_i32 s4, s3, 0x128b0
	s_waitcnt lgkmcnt(1)
	v_pk_fma_f32 v[30:31], v[100:101], v[34:35], v[30:31] op_sel_hi:[1,0,1]
	v_mov_b32_e32 v23, s4
	v_pk_fma_f32 v[30:31], v[102:103], v[34:35], v[30:31] op_sel:[0,1,0]
	v_mov_b32_e32 v34, v37
	v_pk_fma_f32 v[30:31], v[104:105], v[36:37], v[30:31] op_sel_hi:[1,0,1]
	ds_read_b128 v[42:45], v23
	v_pk_fma_f32 v[30:31], v[106:107], v[34:35], v[30:31] op_sel_hi:[1,0,1]
	s_waitcnt lgkmcnt(1)
	v_mov_b32_e32 v34, v41
	v_pk_fma_f32 v[30:31], v[108:109], v[38:39], v[30:31] op_sel_hi:[1,0,1]
	v_pk_mul_f32 v[32:33], v[72:73], v[46:47]
	v_pk_fma_f32 v[30:31], v[110:111], v[38:39], v[30:31] op_sel:[0,1,0]
	s_add_i32 s4, s3, 0x128c0
	v_pk_fma_f32 v[30:31], v[112:113], v[40:41], v[30:31] op_sel_hi:[1,0,1]
	s_nop 0
	v_pk_fma_f32 v[30:31], v[114:115], v[34:35], v[30:31] op_sel_hi:[1,0,1]
	s_waitcnt lgkmcnt(0)
	v_mov_b32_e32 v34, v45
	v_pk_fma_f32 v[30:31], v[116:117], v[42:43], v[30:31] op_sel_hi:[1,0,1]
	s_nop 0
	v_pk_fma_f32 v[30:31], v[118:119], v[42:43], v[30:31] op_sel:[0,1,0]
	s_nop 0
	v_pk_fma_f32 v[30:31], v[120:121], v[44:45], v[30:31] op_sel_hi:[1,0,1]
	s_nop 0
	v_pk_fma_f32 v[30:31], v[122:123], v[34:35], v[30:31] op_sel_hi:[1,0,1]
	v_pk_fma_f32 v[34:35], v[70:71], v[46:47], v[32:33] op_sel:[0,0,1] op_sel_hi:[1,1,0]
	v_pk_fma_f32 v[32:33], v[70:71], v[46:47], v[32:33] op_sel:[0,0,1] op_sel_hi:[1,1,0] neg_lo:[0,0,1] neg_hi:[0,0,1]
	s_nop 0
	v_mov_b32_e32 v35, v33
	v_pk_add_f32 v[46:47], v[34:35], v[30:31]
	s_nop 0
	v_bfe_u32 v23, v47, 16, 1
	v_add3_u32 v23, v47, v23, s33
	ds_write_b16_d16_hi v22, v23 offset:544
	v_bfe_u32 v23, v46, 16, 1
	v_add3_u32 v23, v46, v23, s33
	ds_write_b16_d16_hi v22, v23 offset:672
	v_mov_b32_e32 v23, s4
	ds_read_b128 v[30:33], v23
	s_add_i32 s4, s3, 0x128d0
	v_mov_b32_e32 v23, s4
	ds_read_b128 v[34:37], v23
	s_add_i32 s4, s3, 0x128e0
	s_waitcnt lgkmcnt(1)
	v_pk_fma_f32 v[48:49], v[74:75], v[30:31], 0 op_sel_hi:[1,0,0]
	v_mov_b32_e32 v23, s4
	v_pk_fma_f32 v[30:31], v[76:77], v[30:31], v[48:49] op_sel:[0,1,0]
	ds_read_b128 v[38:41], v23
	v_pk_fma_f32 v[30:31], v[78:79], v[32:33], v[30:31] op_sel_hi:[1,0,1]
	v_mov_b32_e32 v32, v33
	v_pk_fma_f32 v[30:31], v[98:99], v[32:33], v[30:31] op_sel_hi:[1,0,1]
	s_add_i32 s3, s3, 0x128f0
	s_waitcnt lgkmcnt(1)
	v_pk_fma_f32 v[30:31], v[100:101], v[34:35], v[30:31] op_sel_hi:[1,0,1]
	v_mov_b32_e32 v23, s3
	v_pk_fma_f32 v[30:31], v[102:103], v[34:35], v[30:31] op_sel:[0,1,0]
	v_mov_b32_e32 v34, v37
	v_pk_fma_f32 v[30:31], v[104:105], v[36:37], v[30:31] op_sel_hi:[1,0,1]
	ds_read_b128 v[42:45], v23
	v_pk_fma_f32 v[30:31], v[106:107], v[34:35], v[30:31] op_sel_hi:[1,0,1]
	s_waitcnt lgkmcnt(1)
	v_mov_b32_e32 v34, v41
	v_pk_fma_f32 v[30:31], v[108:109], v[38:39], v[30:31] op_sel_hi:[1,0,1]
	v_pk_mul_f32 v[32:33], v[72:73], v[46:47]
	v_pk_fma_f32 v[30:31], v[110:111], v[38:39], v[30:31] op_sel:[0,1,0]
	s_cmp_lg_u32 s1, 0
	v_pk_fma_f32 v[30:31], v[112:113], v[40:41], v[30:31] op_sel_hi:[1,0,1]
	s_nop 0
	v_pk_fma_f32 v[30:31], v[114:115], v[34:35], v[30:31] op_sel_hi:[1,0,1]
	s_waitcnt lgkmcnt(0)
	v_mov_b32_e32 v34, v45
	v_pk_fma_f32 v[30:31], v[116:117], v[42:43], v[30:31] op_sel_hi:[1,0,1]
	s_nop 0
	v_pk_fma_f32 v[30:31], v[118:119], v[42:43], v[30:31] op_sel:[0,1,0]
	s_nop 0
	v_pk_fma_f32 v[30:31], v[120:121], v[44:45], v[30:31] op_sel_hi:[1,0,1]
	s_nop 0
	v_pk_fma_f32 v[30:31], v[122:123], v[34:35], v[30:31] op_sel_hi:[1,0,1]
	v_pk_fma_f32 v[34:35], v[70:71], v[46:47], v[32:33] op_sel:[0,0,1] op_sel_hi:[1,1,0]
	v_pk_fma_f32 v[32:33], v[70:71], v[46:47], v[32:33] op_sel:[0,0,1] op_sel_hi:[1,1,0] neg_lo:[0,0,1] neg_hi:[0,0,1]
	s_nop 0
	v_mov_b32_e32 v35, v33
	v_pk_add_f32 v[38:39], v[34:35], v[30:31]
	s_nop 0
	v_bfe_u32 v23, v39, 16, 1
	v_add3_u32 v23, v39, v23, s33
	ds_write_b16_d16_hi v22, v23 offset:816
	v_bfe_u32 v23, v38, 16, 1
	v_add3_u32 v23, v38, v23, s33
	ds_write_b16_d16_hi v22, v23 offset:944
	v_add_u32_e32 v22, 0x440, v22
	s_cbranch_scc1 .LBB0_184
; DI unsigned pk2(float lo, float hi) { f32x2 v = {lo, hi}; bf16x2_t b = __builtin_convertvector(v, bf16x2_t); return __builtin_bit_cast(unsigned, b); }
; DI float bflo(unsigned w) { return __uint_as_float(w << 16); }
; DI float bfhi(unsigned w) { return __uint_as_float(w & 0xffff0000u); }
; DI float geluf_(float x) { const float a = 0.7978845608028654f * (x + 0.044715f * x * x * x); const float t = 1.f - 2.f * __builtin_amdgcn_rcpf(__expf(2.f * a) + 1.f); return 0.5f * x * (1.f + t); }
; #define MFMA16(a, b, c) __builtin_amdgcn_mfma_f32_16x16x32_bf16((a), (b), (c), 0, 0, 0)
; DI void ssm_s3(CArgs& a, int l, int it, int lane, LAS bf16_t* Xs  , LAS bf16_t* Us) {
;     ...
;         for (int m = 0; m < 2; ++m) {
;             float zz = 0.f; asm volatile("" : "+v"(zz)); f32x4 acc = {zz, zz, zz, zz};
; #pragma unroll
;             for (int kk = 0; kk < 4; ++kk) { const bf16x8 xf = lds_b128(Xs + (16 * m + fr) * 136 + 32 * kk + 8 * fq); acc = MFMA16(cf[kk], xf, acc); }
;             const size_t tg = t0 + 32 * sub + 16 * m + fr;
;             const u32x2 uw = *(const u32x2*)(zb + tg * NZ + ZU + g * 16 + 4 * fq);
;             const float y0 = geluf_(acc[0] + dsk[0] * bflo(uw.x)), y1 = geluf_(acc[1] + dsk[1] * bfhi(uw.x)), y2 = geluf_(acc[2] + dsk[2] * bflo(uw.y)), y3 = geluf_(acc[3] + dsk[3] * bfhi(uw.y));
;             u32x2 ow; ow.x = pk2(y0, y1); ow.y = pk2(y2, y3);
;             *(u32x2*)(gb + tg * 512 + g * 16 + 4 * fq) = ow;
	v_mov_b32_e32 v30, v81
	s_waitcnt lgkmcnt(0)
	ds_read_b128 v[34:37], v126
	v_mov_b32_e32 v31, v30
	v_mov_b32_e32 v32, v30
	v_mov_b32_e32 v33, v30
	v_or_b32_e32 v40, 64, v26
	v_mad_u64_u32 v[22:23], s[4:5], v40, s55, v[28:29]
	s_waitcnt lgkmcnt(0)
	v_mfma_f32_16x16x32_bf16 v[30:33], v[4:7], v[34:37], v[30:33]
	ds_read_b128 v[34:37], v126 offset:64
	v_mad_i32_i24 v23, v27, s55, v23
	v_mov_b32_e32 v41, v27
	s_waitcnt lgkmcnt(0)
	v_mfma_f32_16x16x32_bf16 v[30:33], v[8:11], v[34:37], v[30:33]
	ds_read_b128 v[34:37], v126 offset:128
	s_movk_i32 s1, 0xf800
	s_waitcnt lgkmcnt(0)
	v_mfma_f32_16x16x32_bf16 v[30:33], v[12:15], v[34:37], v[30:33]
	ds_read_b128 v[34:37], v126 offset:192
	s_waitcnt lgkmcnt(0)
	v_mfma_f32_16x16x32_bf16 v[30:33], v[16:19], v[34:37], v[30:33]
	v_add_co_u32_e32 v22, vcc, s79, v22
	s_waitcnt vmcnt(3)
	v_mov_b32_e32 v34, v240
	v_mov_b32_e32 v35, v241
	v_lshlrev_b32_e32 v36, 16, v34
	v_and_b32_e32 v37, 0xffff0000, v34
	s_nop 2
	v_pk_fma_f32 v[30:31], v[0:1], v[36:37], v[30:31]
	v_addc_co_u32_e32 v23, vcc, 0, v23, vcc
	v_mul_f32_e32 v34, 0x3d372713, v30
	v_mul_f32_e32 v34, v30, v34
	v_fma_f32 v34, v30, v34, v30
	v_mul_f32_e32 v34, 0x3f4c422a, v34
	v_add_f32_e32 v34, v34, v34
	v_mul_f32_e32 v34, 0x3fb8aa3b, v34
	v_exp_f32_e32 v34, v34
	s_nop 0
	v_add_f32_e32 v34, 1.0, v34
	v_rcp_f32_e32 v36, v34
	v_mul_f32_e32 v34, 0x3d372713, v31
	v_mul_f32_e32 v34, v31, v34
	v_fma_f32 v34, v31, v34, v31
	v_mul_f32_e32 v34, 0x3f4c422a, v34
	v_add_f32_e32 v34, v34, v34
	v_mul_f32_e32 v34, 0x3fb8aa3b, v34
	v_exp_f32_e32 v34, v34
	v_pk_mul_f32 v[30:31], v[30:31], 0.5 op_sel_hi:[1,0]
	v_add_f32_e32 v34, 1.0, v34
	v_rcp_f32_e32 v37, v34
	v_lshlrev_b32_e32 v34, 16, v35
	v_and_b32_e32 v35, 0xffff0000, v35
	v_pk_fma_f32 v[32:33], v[2:3], v[34:35], v[32:33]
	v_pk_fma_f32 v[36:37], v[36:37], 2.0, 1.0 op_sel_hi:[1,0,0] neg_lo:[1,0,0] neg_hi:[1,0,0]
	v_mul_f32_e32 v34, 0x3d372713, v32
	v_mul_f32_e32 v35, 0x3d372713, v33
	v_mul_f32_e32 v34, v32, v34
	v_mul_f32_e32 v35, v33, v35
	v_fma_f32 v34, v32, v34, v32
	v_fma_f32 v35, v33, v35, v33
	v_mul_f32_e32 v34, 0x3f4c422a, v34
	v_mul_f32_e32 v35, 0x3f4c422a, v35
	v_add_f32_e32 v34, v34, v34
	v_add_f32_e32 v35, v35, v35
	v_mul_f32_e32 v34, 0x3fb8aa3b, v34
	v_mul_f32_e32 v35, 0x3fb8aa3b, v35
	v_exp_f32_e32 v34, v34
	v_exp_f32_e32 v35, v35
	v_pk_add_f32 v[36:37], v[36:37], 1.0 op_sel_hi:[1,0]
	v_pk_mul_f32 v[32:33], v[32:33], 0.5 op_sel_hi:[1,0]
	v_add_f32_e32 v34, 1.0, v34
	v_add_f32_e32 v35, 1.0, v35
	v_rcp_f32_e32 v34, v34
	v_rcp_f32_e32 v35, v35
	v_pk_mul_f32 v[30:31], v[30:31], v[36:37]
	v_pk_fma_f32 v[34:35], v[34:35], 2.0, 1.0 op_sel_hi:[1,0,0] neg_lo:[1,0,0] neg_hi:[1,0,0]
	s_nop 0
	v_pk_add_f32 v[34:35], v[34:35], 1.0 op_sel_hi:[1,0]
	v_cvt_pk_bf16_f32 v30, v30, v31
	v_pk_mul_f32 v[32:33], v[32:33], v[34:35]
	s_nop 0
	v_cvt_pk_bf16_f32 v31, v32, v33
	v_lshlrev_b64 v[32:33], 10, v[40:41]
	v_lshl_add_u64 v[32:33], v[24:25], 0, v[32:33]
	global_store_dwordx2 v[32:33], v[30:31], off
	v_mov_b32_e32 v30, v81
	ds_read_b128 v[34:37], v126 offset:4352
	v_mov_b32_e32 v31, v30
	v_mov_b32_e32 v32, v30
	v_mov_b32_e32 v33, v30
	s_waitcnt lgkmcnt(0)
	s_nop 0
	v_mfma_f32_16x16x32_bf16 v[30:33], v[4:7], v[34:37], v[30:33]
	ds_read_b128 v[34:37], v126 offset:4416
	s_waitcnt lgkmcnt(0)
	v_mfma_f32_16x16x32_bf16 v[30:33], v[8:11], v[34:37], v[30:33]
	ds_read_b128 v[34:37], v126 offset:4480
	s_waitcnt lgkmcnt(0)
	v_mfma_f32_16x16x32_bf16 v[30:33], v[12:15], v[34:37], v[30:33]
	ds_read_b128 v[34:37], v126 offset:4544
	s_waitcnt lgkmcnt(0)
	v_mfma_f32_16x16x32_bf16 v[30:33], v[16:19], v[34:37], v[30:33]
	s_waitcnt vmcnt(2)
	v_mov_b32_e32 v22, v242
	v_mov_b32_e32 v23, v243
	v_lshlrev_b32_e32 v34, 16, v22
	v_and_b32_e32 v35, 0xffff0000, v22
	s_nop 4
	v_pk_fma_f32 v[30:31], v[0:1], v[34:35], v[30:31]
	s_nop 0
	v_mul_f32_e32 v22, 0x3d372713, v30
	v_mul_f32_e32 v22, v30, v22
	v_fma_f32 v22, v30, v22, v30
	v_mul_f32_e32 v22, 0x3f4c422a, v22
	v_add_f32_e32 v22, v22, v22
	v_mul_f32_e32 v22, 0x3fb8aa3b, v22
	v_exp_f32_e32 v22, v22
	s_nop 0
	v_add_f32_e32 v22, 1.0, v22
	v_rcp_f32_e32 v34, v22
	v_mul_f32_e32 v22, 0x3d372713, v31
	v_mul_f32_e32 v22, v31, v22
	v_fma_f32 v22, v31, v22, v31
	v_mul_f32_e32 v22, 0x3f4c422a, v22
	v_add_f32_e32 v22, v22, v22
	v_mul_f32_e32 v22, 0x3fb8aa3b, v22
	v_exp_f32_e32 v22, v22
	v_pk_mul_f32 v[30:31], v[30:31], 0.5 op_sel_hi:[1,0]
	v_add_f32_e32 v22, 1.0, v22
	v_rcp_f32_e32 v35, v22
	v_lshlrev_b32_e32 v22, 16, v23
	v_and_b32_e32 v23, 0xffff0000, v23
	v_pk_fma_f32 v[22:23], v[2:3], v[22:23], v[32:33]
	v_pk_fma_f32 v[34:35], v[34:35], 2.0, 1.0 op_sel_hi:[1,0,0] neg_lo:[1,0,0] neg_hi:[1,0,0]
	v_mul_f32_e32 v32, 0x3d372713, v22
	v_mul_f32_e32 v33, 0x3d372713, v23
	v_mul_f32_e32 v32, v22, v32
	v_mul_f32_e32 v33, v23, v33
	v_fma_f32 v32, v22, v32, v22
	v_fma_f32 v33, v23, v33, v23
	v_mul_f32_e32 v32, 0x3f4c422a, v32
	v_mul_f32_e32 v33, 0x3f4c422a, v33
	v_add_f32_e32 v32, v32, v32
	v_add_f32_e32 v33, v33, v33
	v_mul_f32_e32 v32, 0x3fb8aa3b, v32
	v_mul_f32_e32 v33, 0x3fb8aa3b, v33
	v_exp_f32_e32 v32, v32
	v_exp_f32_e32 v33, v33
	v_pk_add_f32 v[34:35], v[34:35], 1.0 op_sel_hi:[1,0]
	v_pk_mul_f32 v[22:23], v[22:23], 0.5 op_sel_hi:[1,0]
	v_add_f32_e32 v32, 1.0, v32
	v_add_f32_e32 v33, 1.0, v33
	v_rcp_f32_e32 v32, v32
	v_rcp_f32_e32 v33, v33
	v_pk_mul_f32 v[30:31], v[30:31], v[34:35]
	v_pk_fma_f32 v[32:33], v[32:33], 2.0, 1.0 op_sel_hi:[1,0,0] neg_lo:[1,0,0] neg_hi:[1,0,0]
	s_nop 0
	v_pk_add_f32 v[32:33], v[32:33], 1.0 op_sel_hi:[1,0]
	s_nop 0
	v_pk_mul_f32 v[32:33], v[22:23], v[32:33]
	v_cvt_pk_bf16_f32 v22, v30, v31
	v_or_b32_e32 v30, 0x14000, v20
	v_mov_b32_e32 v31, v21
	v_cvt_pk_bf16_f32 v23, v32, v33
	v_lshl_add_u64 v[30:31], v[24:25], 0, v[30:31]
	global_store_dwordx2 v[30:31], v[22:23], off
	s_waitcnt lgkmcnt(0)
	v_mov_b32_e32 v22, v124
; #define LAS __attribute__((address_space(3)))
; DI unsigned f2bf(float f) { unsigned u = __builtin_bit_cast(unsigned, f); return (u + 0x7fffu + ((u >> 16) & 1u)) >> 16; }
; DI void ssm_step_lds(const SsmC& c, const LAS bf16_t* up_, float& xr, float& xi) {
;     const LAS f32x4* up = (const LAS f32x4*)up_;
;     const f32x4 u0 = up[0], u1 = up[1], u2 = up[2], u3 = up[3];
;     float sr = 0.f, si = 0.f;
; #pragma unroll
;     for (int e = 0; e < 4; ++e) { sr += c.bbr[e] * u0[e]; si += c.bbi[e] * u0[e]; }
; #pragma unroll
;     for (int e = 0; e < 4; ++e) { sr += c.bbr[4 + e] * u1[e]; si += c.bbi[4 + e] * u1[e]; }
; #pragma unroll
;     for (int e = 0; e < 4; ++e) { sr += c.bbr[8 + e] * u2[e]; si += c.bbi[8 + e] * u2[e]; }
; #pragma unroll
;     for (int e = 0; e < 4; ++e) { sr += c.bbr[12 + e] * u3[e]; si += c.bbi[12 + e] * u3[e]; }
;     const float nxr = c.ar * xr - c.ai * xi + sr, nxi = c.ar * xi + c.ai * xr + si; xr = nxr; xi = nxi;
; }
; DI void ssm_s3(CArgs& a, int l, int it, int lane, LAS bf16_t* Xs  , LAS bf16_t* Us) {
;     ...
;         for (int tt = 0; tt < 32; ++tt) { ssm_step_lds(c, Us + (32 * sub + tt) * 32, xr, xi);
;             Xs[tt * 136 + lane] = (bf16_t)f2bf(xr); Xs[tt * 136 + 64 + lane] = (bf16_t)f2bf(xi); }
.LBB0_186:
	s_add_i32 s3, s0, s1
	s_add_i32 s4, s3, 0x13000
	v_mov_b32_e32 v23, s4
	ds_read_b128 v[30:33], v23
	s_add_i32 s4, s3, 0x13010
	v_mov_b32_e32 v23, s4
	ds_read_b128 v[34:37], v23
	s_add_i32 s4, s3, 0x13020
	s_waitcnt lgkmcnt(1)
	v_pk_fma_f32 v[48:49], v[74:75], v[30:31], 0 op_sel_hi:[1,0,0]
	v_mov_b32_e32 v23, s4
	v_pk_fma_f32 v[30:31], v[76:77], v[30:31], v[48:49] op_sel:[0,1,0]
	ds_read_b128 v[40:43], v23
	v_pk_fma_f32 v[30:31], v[78:79], v[32:33], v[30:31] op_sel_hi:[1,0,1]
	v_mov_b32_e32 v32, v33
	v_pk_fma_f32 v[30:31], v[98:99], v[32:33], v[30:31] op_sel_hi:[1,0,1]
	s_add_i32 s4, s3, 0x13030
	s_waitcnt lgkmcnt(1)
	v_pk_fma_f32 v[30:31], v[100:101], v[34:35], v[30:31] op_sel_hi:[1,0,1]
	v_mov_b32_e32 v23, s4
	v_pk_fma_f32 v[30:31], v[102:103], v[34:35], v[30:31] op_sel:[0,1,0]
	v_mov_b32_e32 v34, v37
	v_pk_fma_f32 v[30:31], v[104:105], v[36:37], v[30:31] op_sel_hi:[1,0,1]
	ds_read_b128 v[44:47], v23
	v_pk_fma_f32 v[30:31], v[106:107], v[34:35], v[30:31] op_sel_hi:[1,0,1]
	s_waitcnt lgkmcnt(1)
	v_mov_b32_e32 v34, v43
	v_pk_fma_f32 v[30:31], v[108:109], v[40:41], v[30:31] op_sel_hi:[1,0,1]
	v_pk_mul_f32 v[32:33], v[72:73], v[38:39]
	v_pk_fma_f32 v[30:31], v[110:111], v[40:41], v[30:31] op_sel:[0,1,0]
	s_add_i32 s4, s3, 0x13040
	v_pk_fma_f32 v[30:31], v[112:113], v[42:43], v[30:31] op_sel_hi:[1,0,1]
	s_addk_i32 s1, 0x100
	v_pk_fma_f32 v[30:31], v[114:115], v[34:35], v[30:31] op_sel_hi:[1,0,1]
	s_waitcnt lgkmcnt(0)
	v_mov_b32_e32 v34, v47
	v_pk_fma_f32 v[30:31], v[116:117], v[44:45], v[30:31] op_sel_hi:[1,0,1]
	s_nop 0
	v_pk_fma_f32 v[30:31], v[118:119], v[44:45], v[30:31] op_sel:[0,1,0]
	s_nop 0
	v_pk_fma_f32 v[30:31], v[120:121], v[46:47], v[30:31] op_sel_hi:[1,0,1]
	s_nop 0
	v_pk_fma_f32 v[30:31], v[122:123], v[34:35], v[30:31] op_sel_hi:[1,0,1]
	v_pk_fma_f32 v[34:35], v[70:71], v[38:39], v[32:33] op_sel:[0,0,1] op_sel_hi:[1,1,0]
	v_pk_fma_f32 v[32:33], v[70:71], v[38:39], v[32:33] op_sel:[0,0,1] op_sel_hi:[1,1,0] neg_lo:[0,0,1] neg_hi:[0,0,1]
	s_nop 0
	v_mov_b32_e32 v35, v33
	v_pk_add_f32 v[46:47], v[34:35], v[30:31]
	s_nop 0
	v_bfe_u32 v23, v47, 16, 1
	v_add3_u32 v23, v47, v23, s33
	ds_write_b16_d16_hi v22, v23
	v_bfe_u32 v23, v46, 16, 1
	v_add3_u32 v23, v46, v23, s33
	ds_write_b16_d16_hi v22, v23 offset:128
	v_mov_b32_e32 v23, s4
	ds_read_b128 v[30:33], v23
	s_add_i32 s4, s3, 0x13050
	v_mov_b32_e32 v23, s4
	ds_read_b128 v[34:37], v23
	s_add_i32 s4, s3, 0x13060
	s_waitcnt lgkmcnt(1)
	v_pk_fma_f32 v[48:49], v[74:75], v[30:31], 0 op_sel_hi:[1,0,0]
	v_mov_b32_e32 v23, s4
	v_pk_fma_f32 v[30:31], v[76:77], v[30:31], v[48:49] op_sel:[0,1,0]
	ds_read_b128 v[38:41], v23
	v_pk_fma_f32 v[30:31], v[78:79], v[32:33], v[30:31] op_sel_hi:[1,0,1]
	v_mov_b32_e32 v32, v33
	v_pk_fma_f32 v[30:31], v[98:99], v[32:33], v[30:31] op_sel_hi:[1,0,1]
	s_add_i32 s4, s3, 0x13070
	s_waitcnt lgkmcnt(1)
	v_pk_fma_f32 v[30:31], v[100:101], v[34:35], v[30:31] op_sel_hi:[1,0,1]
	v_mov_b32_e32 v23, s4
	v_pk_fma_f32 v[30:31], v[102:103], v[34:35], v[30:31] op_sel:[0,1,0]
	v_mov_b32_e32 v34, v37
	v_pk_fma_f32 v[30:31], v[104:105], v[36:37], v[30:31] op_sel_hi:[1,0,1]
	ds_read_b128 v[42:45], v23
	v_pk_fma_f32 v[30:31], v[106:107], v[34:35], v[30:31] op_sel_hi:[1,0,1]
	s_waitcnt lgkmcnt(1)
	v_mov_b32_e32 v34, v41
	v_pk_fma_f32 v[30:31], v[108:109], v[38:39], v[30:31] op_sel_hi:[1,0,1]
	v_pk_mul_f32 v[32:33], v[72:73], v[46:47]
	v_pk_fma_f32 v[30:31], v[110:111], v[38:39], v[30:31] op_sel:[0,1,0]
	s_add_i32 s4, s3, 0x13080
	v_pk_fma_f32 v[30:31], v[112:113], v[40:41], v[30:31] op_sel_hi:[1,0,1]
	s_nop 0
	v_pk_fma_f32 v[30:31], v[114:115], v[34:35], v[30:31] op_sel_hi:[1,0,1]
	s_waitcnt lgkmcnt(0)
	v_mov_b32_e32 v34, v45
	v_pk_fma_f32 v[30:31], v[116:117], v[42:43], v[30:31] op_sel_hi:[1,0,1]
	s_nop 0
	v_pk_fma_f32 v[30:31], v[118:119], v[42:43], v[30:31] op_sel:[0,1,0]
	s_nop 0
	v_pk_fma_f32 v[30:31], v[120:121], v[44:45], v[30:31] op_sel_hi:[1,0,1]
	s_nop 0
	v_pk_fma_f32 v[30:31], v[122:123], v[34:35], v[30:31] op_sel_hi:[1,0,1]
	v_pk_fma_f32 v[34:35], v[70:71], v[46:47], v[32:33] op_sel:[0,0,1] op_sel_hi:[1,1,0]
	v_pk_fma_f32 v[32:33], v[70:71], v[46:47], v[32:33] op_sel:[0,0,1] op_sel_hi:[1,1,0] neg_lo:[0,0,1] neg_hi:[0,0,1]
	s_nop 0
	v_mov_b32_e32 v35, v33
	v_pk_add_f32 v[46:47], v[34:35], v[30:31]
	s_nop 0
	v_bfe_u32 v23, v47, 16, 1
	v_add3_u32 v23, v47, v23, s33
	ds_write_b16_d16_hi v22, v23 offset:272
	v_bfe_u32 v23, v46, 16, 1
	v_add3_u32 v23, v46, v23, s33
	ds_write_b16_d16_hi v22, v23 offset:400
	v_mov_b32_e32 v23, s4
	ds_read_b128 v[30:33], v23
	s_add_i32 s4, s3, 0x13090
	v_mov_b32_e32 v23, s4
	ds_read_b128 v[34:37], v23
	s_add_i32 s4, s3, 0x130a0
	s_waitcnt lgkmcnt(1)
	v_pk_fma_f32 v[48:49], v[74:75], v[30:31], 0 op_sel_hi:[1,0,0]
	v_mov_b32_e32 v23, s4
	v_pk_fma_f32 v[30:31], v[76:77], v[30:31], v[48:49] op_sel:[0,1,0]
	ds_read_b128 v[38:41], v23
	v_pk_fma_f32 v[30:31], v[78:79], v[32:33], v[30:31] op_sel_hi:[1,0,1]
	v_mov_b32_e32 v32, v33
	v_pk_fma_f32 v[30:31], v[98:99], v[32:33], v[30:31] op_sel_hi:[1,0,1]
	s_add_i32 s4, s3, 0x130b0
	s_waitcnt lgkmcnt(1)
	v_pk_fma_f32 v[30:31], v[100:101], v[34:35], v[30:31] op_sel_hi:[1,0,1]
	v_mov_b32_e32 v23, s4
	v_pk_fma_f32 v[30:31], v[102:103], v[34:35], v[30:31] op_sel:[0,1,0]
	v_mov_b32_e32 v34, v37
	v_pk_fma_f32 v[30:31], v[104:105], v[36:37], v[30:31] op_sel_hi:[1,0,1]
	ds_read_b128 v[42:45], v23
	v_pk_fma_f32 v[30:31], v[106:107], v[34:35], v[30:31] op_sel_hi:[1,0,1]
	s_waitcnt lgkmcnt(1)
	v_mov_b32_e32 v34, v41
	v_pk_fma_f32 v[30:31], v[108:109], v[38:39], v[30:31] op_sel_hi:[1,0,1]
	v_pk_mul_f32 v[32:33], v[72:73], v[46:47]
	v_pk_fma_f32 v[30:31], v[110:111], v[38:39], v[30:31] op_sel:[0,1,0]
	s_add_i32 s4, s3, 0x130c0
	v_pk_fma_f32 v[30:31], v[112:113], v[40:41], v[30:31] op_sel_hi:[1,0,1]
	s_nop 0
	v_pk_fma_f32 v[30:31], v[114:115], v[34:35], v[30:31] op_sel_hi:[1,0,1]
	s_waitcnt lgkmcnt(0)
; #define LAS __attribute__((address_space(3)))
; DI unsigned f2bf(float f) { unsigned u = __builtin_bit_cast(unsigned, f); return (u + 0x7fffu + ((u >> 16) & 1u)) >> 16; }
; DI void ssm_step_lds(const SsmC& c, const LAS bf16_t* up_, float& xr, float& xi) {
;     const LAS f32x4* up = (const LAS f32x4*)up_;
;     const f32x4 u0 = up[0], u1 = up[1], u2 = up[2], u3 = up[3];
;     float sr = 0.f, si = 0.f;
; #pragma unroll
;     for (int e = 0; e < 4; ++e) { sr += c.bbr[e] * u0[e]; si += c.bbi[e] * u0[e]; }
; #pragma unroll
;     for (int e = 0; e < 4; ++e) { sr += c.bbr[4 + e] * u1[e]; si += c.bbi[4 + e] * u1[e]; }
; #pragma unroll
;     for (int e = 0; e < 4; ++e) { sr += c.bbr[8 + e] * u2[e]; si += c.bbi[8 + e] * u2[e]; }
; #pragma unroll
;     for (int e = 0; e < 4; ++e) { sr += c.bbr[12 + e] * u3[e]; si += c.bbi[12 + e] * u3[e]; }
;     const float nxr = c.ar * xr - c.ai * xi + sr, nxi = c.ar * xi + c.ai * xr + si; xr = nxr; xi = nxi;
; }
; DI void ssm_s3(CArgs& a, int l, int it, int lane, LAS bf16_t* Xs  , LAS bf16_t* Us) {
;     ...
;         for (int tt = 0; tt < 32; ++tt) { ssm_step_lds(c, Us + (32 * sub + tt) * 32, xr, xi);
;             Xs[tt * 136 + lane] = (bf16_t)f2bf(xr); Xs[tt * 136 + 64 + lane] = (bf16_t)f2bf(xi); }
	v_mov_b32_e32 v34, v45
	v_pk_fma_f32 v[30:31], v[116:117], v[42:43], v[30:31] op_sel_hi:[1,0,1]
	s_nop 0
	v_pk_fma_f32 v[30:31], v[118:119], v[42:43], v[30:31] op_sel:[0,1,0]
	s_nop 0
	v_pk_fma_f32 v[30:31], v[120:121], v[44:45], v[30:31] op_sel_hi:[1,0,1]
	s_nop 0
	v_pk_fma_f32 v[30:31], v[122:123], v[34:35], v[30:31] op_sel_hi:[1,0,1]
	v_pk_fma_f32 v[34:35], v[70:71], v[46:47], v[32:33] op_sel:[0,0,1] op_sel_hi:[1,1,0]
	v_pk_fma_f32 v[32:33], v[70:71], v[46:47], v[32:33] op_sel:[0,0,1] op_sel_hi:[1,1,0] neg_lo:[0,0,1] neg_hi:[0,0,1]
	s_nop 0
	v_mov_b32_e32 v35, v33
	v_pk_add_f32 v[46:47], v[34:35], v[30:31]
	s_nop 0
	v_bfe_u32 v23, v47, 16, 1
	v_add3_u32 v23, v47, v23, s33
	ds_write_b16_d16_hi v22, v23 offset:544
	v_bfe_u32 v23, v46, 16, 1
	v_add3_u32 v23, v46, v23, s33
	ds_write_b16_d16_hi v22, v23 offset:672
	v_mov_b32_e32 v23, s4
	ds_read_b128 v[30:33], v23
	s_add_i32 s4, s3, 0x130d0
	v_mov_b32_e32 v23, s4
	ds_read_b128 v[34:37], v23
	s_add_i32 s4, s3, 0x130e0
	s_waitcnt lgkmcnt(1)
	v_pk_fma_f32 v[48:49], v[74:75], v[30:31], 0 op_sel_hi:[1,0,0]
	v_mov_b32_e32 v23, s4
	v_pk_fma_f32 v[30:31], v[76:77], v[30:31], v[48:49] op_sel:[0,1,0]
	ds_read_b128 v[38:41], v23
	v_pk_fma_f32 v[30:31], v[78:79], v[32:33], v[30:31] op_sel_hi:[1,0,1]
	v_mov_b32_e32 v32, v33
	v_pk_fma_f32 v[30:31], v[98:99], v[32:33], v[30:31] op_sel_hi:[1,0,1]
	s_add_i32 s3, s3, 0x130f0
	s_waitcnt lgkmcnt(1)
	v_pk_fma_f32 v[30:31], v[100:101], v[34:35], v[30:31] op_sel_hi:[1,0,1]
	v_mov_b32_e32 v23, s3
	v_pk_fma_f32 v[30:31], v[102:103], v[34:35], v[30:31] op_sel:[0,1,0]
	v_mov_b32_e32 v34, v37
	v_pk_fma_f32 v[30:31], v[104:105], v[36:37], v[30:31] op_sel_hi:[1,0,1]
	ds_read_b128 v[42:45], v23
	v_pk_fma_f32 v[30:31], v[106:107], v[34:35], v[30:31] op_sel_hi:[1,0,1]
	s_waitcnt lgkmcnt(1)
	v_mov_b32_e32 v34, v41
	v_pk_fma_f32 v[30:31], v[108:109], v[38:39], v[30:31] op_sel_hi:[1,0,1]
	v_pk_mul_f32 v[32:33], v[72:73], v[46:47]
	v_pk_fma_f32 v[30:31], v[110:111], v[38:39], v[30:31] op_sel:[0,1,0]
	s_cmp_lg_u32 s1, 0
	v_pk_fma_f32 v[30:31], v[112:113], v[40:41], v[30:31] op_sel_hi:[1,0,1]
	s_nop 0
	v_pk_fma_f32 v[30:31], v[114:115], v[34:35], v[30:31] op_sel_hi:[1,0,1]
	s_waitcnt lgkmcnt(0)
	v_mov_b32_e32 v34, v45
	v_pk_fma_f32 v[30:31], v[116:117], v[42:43], v[30:31] op_sel_hi:[1,0,1]
	s_nop 0
	v_pk_fma_f32 v[30:31], v[118:119], v[42:43], v[30:31] op_sel:[0,1,0]
	s_nop 0
	v_pk_fma_f32 v[30:31], v[120:121], v[44:45], v[30:31] op_sel_hi:[1,0,1]
	s_nop 0
	v_pk_fma_f32 v[30:31], v[122:123], v[34:35], v[30:31] op_sel_hi:[1,0,1]
	v_pk_fma_f32 v[34:35], v[70:71], v[46:47], v[32:33] op_sel:[0,0,1] op_sel_hi:[1,1,0]
	v_pk_fma_f32 v[32:33], v[70:71], v[46:47], v[32:33] op_sel:[0,0,1] op_sel_hi:[1,1,0] neg_lo:[0,0,1] neg_hi:[0,0,1]
	s_nop 0
	v_mov_b32_e32 v35, v33
	v_pk_add_f32 v[38:39], v[34:35], v[30:31]
	s_nop 0
	v_bfe_u32 v23, v39, 16, 1
	v_add3_u32 v23, v39, v23, s33
	ds_write_b16_d16_hi v22, v23 offset:816
	v_bfe_u32 v23, v38, 16, 1
	v_add3_u32 v23, v38, v23, s33
	ds_write_b16_d16_hi v22, v23 offset:944
	v_add_u32_e32 v22, 0x440, v22
	s_cbranch_scc1 .LBB0_186
; DI unsigned pk2(float lo, float hi) { f32x2 v = {lo, hi}; bf16x2_t b = __builtin_convertvector(v, bf16x2_t); return __builtin_bit_cast(unsigned, b); }
; DI float bflo(unsigned w) { return __uint_as_float(w << 16); }
; DI float bfhi(unsigned w) { return __uint_as_float(w & 0xffff0000u); }
; DI float geluf_(float x) { const float a = 0.7978845608028654f * (x + 0.044715f * x * x * x); const float t = 1.f - 2.f * __builtin_amdgcn_rcpf(__expf(2.f * a) + 1.f); return 0.5f * x * (1.f + t); }
; #define MFMA16(a, b, c) __builtin_amdgcn_mfma_f32_16x16x32_bf16((a), (b), (c), 0, 0, 0)
; DI void ssm_s3(CArgs& a, int l, int it, int lane, LAS bf16_t* Xs  , LAS bf16_t* Us) {
;     ...
;         for (int m = 0; m < 2; ++m) {
;             float zz = 0.f; asm volatile("" : "+v"(zz)); f32x4 acc = {zz, zz, zz, zz};
; #pragma unroll
;             for (int kk = 0; kk < 4; ++kk) { const bf16x8 xf = lds_b128(Xs + (16 * m + fr) * 136 + 32 * kk + 8 * fq); acc = MFMA16(cf[kk], xf, acc); }
;             const size_t tg = t0 + 32 * sub + 16 * m + fr;
;             const u32x2 uw = *(const u32x2*)(zb + tg * NZ + ZU + g * 16 + 4 * fq);
;             const float y0 = geluf_(acc[0] + dsk[0] * bflo(uw.x)), y1 = geluf_(acc[1] + dsk[1] * bfhi(uw.x)), y2 = geluf_(acc[2] + dsk[2] * bflo(uw.y)), y3 = geluf_(acc[3] + dsk[3] * bfhi(uw.y));
;             u32x2 ow; ow.x = pk2(y0, y1); ow.y = pk2(y2, y3);
;             *(u32x2*)(gb + tg * 512 + g * 16 + 4 * fq) = ow;
	v_or_b32_e32 v26, 0x60, v26
	v_mad_u64_u32 v[22:23], s[4:5], v26, s55, v[28:29]
	v_mov_b32_e32 v30, v81
	v_mad_i32_i24 v23, v27, s55, v23
	s_waitcnt lgkmcnt(0)
	ds_read_b128 v[34:37], v126
	v_mov_b32_e32 v31, v30
	v_mov_b32_e32 v32, v30
	v_mov_b32_e32 v33, v30
	v_lshlrev_b64 v[26:27], 10, v[26:27]
	v_lshl_add_u64 v[26:27], v[24:25], 0, v[26:27]
	s_waitcnt lgkmcnt(0)
	v_mfma_f32_16x16x32_bf16 v[30:33], v[4:7], v[34:37], v[30:33]
	ds_read_b128 v[34:37], v126 offset:64
	v_or_b32_e32 v20, 0x1c000, v20
	s_add_i32 s2, s2, s80
	s_waitcnt lgkmcnt(0)
	v_mfma_f32_16x16x32_bf16 v[30:33], v[8:11], v[34:37], v[30:33]
	ds_read_b128 v[34:37], v126 offset:128
	s_cmpk_gt_i32 s2, 0x1fff
	s_waitcnt lgkmcnt(0)
	v_mfma_f32_16x16x32_bf16 v[30:33], v[12:15], v[34:37], v[30:33]
	ds_read_b128 v[34:37], v126 offset:192
	s_waitcnt lgkmcnt(0)
	v_mfma_f32_16x16x32_bf16 v[30:33], v[16:19], v[34:37], v[30:33]
	s_waitcnt vmcnt(1)
	v_mov_b32_e32 v28, v244
	v_mov_b32_e32 v29, v245
	v_lshlrev_b32_e32 v34, 16, v28
	v_and_b32_e32 v35, 0xffff0000, v28
	s_nop 4
	v_pk_fma_f32 v[30:31], v[0:1], v[34:35], v[30:31]
	s_nop 0
	v_mul_f32_e32 v28, 0x3d372713, v30
	v_mul_f32_e32 v28, v30, v28
	v_fma_f32 v28, v30, v28, v30
	v_mul_f32_e32 v28, 0x3f4c422a, v28
	v_add_f32_e32 v28, v28, v28
	v_mul_f32_e32 v28, 0x3fb8aa3b, v28
	v_exp_f32_e32 v28, v28
	s_nop 0
	v_add_f32_e32 v28, 1.0, v28
	v_rcp_f32_e32 v34, v28
	v_mul_f32_e32 v28, 0x3d372713, v31
	v_mul_f32_e32 v28, v31, v28
	v_fma_f32 v28, v31, v28, v31
	v_mul_f32_e32 v28, 0x3f4c422a, v28
	v_add_f32_e32 v28, v28, v28
	v_mul_f32_e32 v28, 0x3fb8aa3b, v28
	v_exp_f32_e32 v28, v28
	v_pk_mul_f32 v[30:31], v[30:31], 0.5 op_sel_hi:[1,0]
	v_add_f32_e32 v28, 1.0, v28
	v_rcp_f32_e32 v35, v28
	v_lshlrev_b32_e32 v28, 16, v29
	v_and_b32_e32 v29, 0xffff0000, v29
	v_pk_fma_f32 v[28:29], v[2:3], v[28:29], v[32:33]
	v_pk_fma_f32 v[34:35], v[34:35], 2.0, 1.0 op_sel_hi:[1,0,0] neg_lo:[1,0,0] neg_hi:[1,0,0]
	v_mul_f32_e32 v32, 0x3d372713, v28
	v_mul_f32_e32 v33, 0x3d372713, v29
	v_mul_f32_e32 v32, v28, v32
	v_mul_f32_e32 v33, v29, v33
	v_fma_f32 v32, v28, v32, v28
	v_fma_f32 v33, v29, v33, v29
	v_mul_f32_e32 v32, 0x3f4c422a, v32
	v_mul_f32_e32 v33, 0x3f4c422a, v33
	v_add_f32_e32 v32, v32, v32
	v_add_f32_e32 v33, v33, v33
	v_mul_f32_e32 v32, 0x3fb8aa3b, v32
	v_mul_f32_e32 v33, 0x3fb8aa3b, v33
	v_exp_f32_e32 v32, v32
	v_exp_f32_e32 v33, v33
	v_pk_add_f32 v[34:35], v[34:35], 1.0 op_sel_hi:[1,0]
	v_pk_mul_f32 v[28:29], v[28:29], 0.5 op_sel_hi:[1,0]
	v_add_f32_e32 v32, 1.0, v32
	v_add_f32_e32 v33, 1.0, v33
	v_rcp_f32_e32 v32, v32
	v_rcp_f32_e32 v33, v33
	v_pk_mul_f32 v[30:31], v[30:31], v[34:35]
	v_pk_fma_f32 v[32:33], v[32:33], 2.0, 1.0 op_sel_hi:[1,0,0] neg_lo:[1,0,0] neg_hi:[1,0,0]
	s_nop 0
	v_pk_add_f32 v[32:33], v[32:33], 1.0 op_sel_hi:[1,0]
	v_cvt_pk_bf16_f32 v30, v30, v31
	v_pk_mul_f32 v[28:29], v[28:29], v[32:33]
	s_nop 0
	v_cvt_pk_bf16_f32 v31, v28, v29
	global_store_dwordx2 v[26:27], v[30:31], off
	v_mov_b32_e32 v26, v81
	ds_read_b128 v[30:33], v126 offset:4352
	v_mov_b32_e32 v27, v26
	v_mov_b32_e32 v28, v26
	v_mov_b32_e32 v29, v26
	s_waitcnt lgkmcnt(0)
	s_nop 0
	v_mfma_f32_16x16x32_bf16 v[4:7], v[4:7], v[30:33], v[26:29]
	s_nop 2
	ds_read_b128 v[26:29], v126 offset:4416
	s_waitcnt lgkmcnt(0)
	v_mfma_f32_16x16x32_bf16 v[4:7], v[8:11], v[26:29], v[4:7]
	ds_read_b128 v[8:11], v126 offset:4480
	s_waitcnt lgkmcnt(0)
	v_mfma_f32_16x16x32_bf16 v[4:7], v[12:15], v[8:11], v[4:7]
	ds_read_b128 v[8:11], v126 offset:4544
	s_waitcnt lgkmcnt(0)
	v_mfma_f32_16x16x32_bf16 v[4:7], v[16:19], v[8:11], v[4:7]
	v_add_co_u32_e32 v8, vcc, s79, v22
	s_nop 1
	v_addc_co_u32_e32 v9, vcc, 0, v23, vcc
	s_waitcnt vmcnt(0)
	v_mov_b32_e32 v8, v246
	v_mov_b32_e32 v9, v247
	v_lshlrev_b32_e32 v10, 16, v8
	v_and_b32_e32 v11, 0xffff0000, v8
	v_pk_fma_f32 v[0:1], v[0:1], v[10:11], v[4:5]
	s_nop 0
	v_mul_f32_e32 v4, 0x3d372713, v0
	v_mul_f32_e32 v5, 0x3d372713, v1
	v_mul_f32_e32 v4, v0, v4
	v_mul_f32_e32 v5, v1, v5
	v_fma_f32 v4, v0, v4, v0
	v_fma_f32 v5, v1, v5, v1
	v_mul_f32_e32 v4, 0x3f4c422a, v4
	v_mul_f32_e32 v5, 0x3f4c422a, v5
	v_add_f32_e32 v4, v4, v4
	v_add_f32_e32 v5, v5, v5
	v_mul_f32_e32 v4, 0x3fb8aa3b, v4
	v_mul_f32_e32 v5, 0x3fb8aa3b, v5
	v_exp_f32_e32 v4, v4
	v_exp_f32_e32 v5, v5
	v_pk_mul_f32 v[0:1], v[0:1], 0.5 op_sel_hi:[1,0]
	v_add_f32_e32 v4, 1.0, v4
	v_add_f32_e32 v5, 1.0, v5
	v_rcp_f32_e32 v4, v4
	v_rcp_f32_e32 v5, v5
	s_nop 0
	v_pk_fma_f32 v[4:5], v[4:5], 2.0, 1.0 op_sel_hi:[1,0,0] neg_lo:[1,0,0] neg_hi:[1,0,0]
	s_nop 0
	v_pk_add_f32 v[4:5], v[4:5], 1.0 op_sel_hi:[1,0]
	s_nop 0
	v_pk_mul_f32 v[0:1], v[0:1], v[4:5]
	v_lshlrev_b32_e32 v4, 16, v9
	v_and_b32_e32 v5, 0xffff0000, v9
	v_pk_fma_f32 v[2:3], v[2:3], v[4:5], v[6:7]
	v_cvt_pk_bf16_f32 v0, v0, v1
	v_mul_f32_e32 v4, 0x3d372713, v2
	v_mul_f32_e32 v5, 0x3d372713, v3
	v_mul_f32_e32 v4, v2, v4
	v_mul_f32_e32 v5, v3, v5
	v_fma_f32 v4, v2, v4, v2
	v_fma_f32 v5, v3, v5, v3
	v_mul_f32_e32 v4, 0x3f4c422a, v4
	v_mul_f32_e32 v5, 0x3f4c422a, v5
	v_add_f32_e32 v4, v4, v4
	v_add_f32_e32 v5, v5, v5
	v_mul_f32_e32 v4, 0x3fb8aa3b, v4
	v_mul_f32_e32 v5, 0x3fb8aa3b, v5
	v_exp_f32_e32 v4, v4
	v_exp_f32_e32 v5, v5
	v_pk_mul_f32 v[2:3], v[2:3], 0.5 op_sel_hi:[1,0]
	v_add_f32_e32 v4, 1.0, v4
	v_add_f32_e32 v5, 1.0, v5
	v_rcp_f32_e32 v4, v4
	v_rcp_f32_e32 v5, v5
	s_nop 0
	v_pk_fma_f32 v[4:5], v[4:5], 2.0, 1.0 op_sel_hi:[1,0,0] neg_lo:[1,0,0] neg_hi:[1,0,0]
	s_nop 0
	v_pk_add_f32 v[4:5], v[4:5], 1.0 op_sel_hi:[1,0]
	s_nop 0
	v_pk_mul_f32 v[2:3], v[2:3], v[4:5]
	s_nop 0
	v_cvt_pk_bf16_f32 v1, v2, v3
	v_lshl_add_u64 v[2:3], v[24:25], 0, v[20:21]
	global_store_dwordx2 v[2:3], v[0:1], off
	s_waitcnt lgkmcnt(0)
	s_cbranch_scc0 .LBB0_179

; #define LAS __attribute__((address_space(3)))
; __global__ void __launch_bounds__(512, 2) fwd_mega(Args a_unused) {
;     extern __shared__ __attribute__((aligned(16))) unsigned char lds_raw[];
;     LAS unsigned char* lds = (LAS unsigned char*)lds_raw;
;     cg::grid_group grid = cg::this_grid();
;     const int G = gridDim.x, bx = blockIdx.x, NGW = G * 8;
	.amdhsa_kernel _Z8fwd_mega4Args
		.amdhsa_group_segment_fixed_size 0
		.amdhsa_private_segment_fixed_size 0
		.amdhsa_kernarg_size 512
		.amdhsa_user_sgpr_count 2
		.amdhsa_user_sgpr_dispatch_ptr 0
		.amdhsa_user_sgpr_queue_ptr 0
		.amdhsa_user_sgpr_kernarg_segment_ptr 1
		.amdhsa_user_sgpr_dispatch_id 0
		.amdhsa_user_sgpr_kernarg_preload_length 0
		.amdhsa_user_sgpr_kernarg_preload_offset 0
		.amdhsa_user_sgpr_private_segment_size 0
		.amdhsa_uses_dynamic_stack 0
		.amdhsa_enable_private_segment 0
		.amdhsa_system_sgpr_workgroup_id_x 1
		.amdhsa_system_sgpr_workgroup_id_y 0
		.amdhsa_system_sgpr_workgroup_id_z 0
		.amdhsa_system_sgpr_workgroup_info 0
		.amdhsa_system_vgpr_workitem_id 2
		.amdhsa_next_free_vgpr 256
		.amdhsa_next_free_sgpr 102
		.amdhsa_accum_offset 256
		.amdhsa_reserve_vcc 1
		.amdhsa_float_round_mode_32 0
		.amdhsa_float_round_mode_16_64 0
		.amdhsa_float_denorm_mode_32 3
		.amdhsa_float_denorm_mode_16_64 3
		.amdhsa_dx10_clamp 1
		.amdhsa_ieee_mode 1
		.amdhsa_fp16_overflow 0
		.amdhsa_tg_split 0
		.amdhsa_exception_fp_ieee_invalid_op 0
		.amdhsa_exception_fp_denorm_src 0
		.amdhsa_exception_fp_ieee_div_zero 0
		.amdhsa_exception_fp_ieee_overflow 0
		.amdhsa_exception_fp_ieee_underflow 0
		.amdhsa_exception_fp_ieee_inexact 0
		.amdhsa_exception_int_div_zero 0
	.end_amdhsa_kernel

; #define LAS __attribute__((address_space(3)))
; __global__ void __launch_bounds__(512, 2) fwd_mega(Args a_unused) {
;     extern __shared__ __attribute__((aligned(16))) unsigned char lds_raw[];
;     LAS unsigned char* lds = (LAS unsigned char*)lds_raw;
;     cg::grid_group grid = cg::this_grid();
;     const int G = gridDim.x, bx = blockIdx.x, NGW = G * 8;
amdhsa.kernels:
  - .agpr_count:     0
    .args:
      - .offset:         0
        .size:           256
        .value_kind:     by_value
      - .offset:         256
        .size:           4
        .value_kind:     hidden_block_count_x
      - .offset:         260
        .size:           4
        .value_kind:     hidden_block_count_y
      - .offset:         264
        .size:           4
        .value_kind:     hidden_block_count_z
      - .offset:         268
        .size:           2
        .value_kind:     hidden_group_size_x
      - .offset:         270
        .size:           2
        .value_kind:     hidden_group_size_y
      - .offset:         272
        .size:           2
        .value_kind:     hidden_group_size_z
      - .offset:         274
        .size:           2
        .value_kind:     hidden_remainder_x
      - .offset:         276
        .size:           2
        .value_kind:     hidden_remainder_y
      - .offset:         278
        .size:           2
        .value_kind:     hidden_remainder_z
      - .offset:         296
        .size:           8
        .value_kind:     hidden_global_offset_x
      - .offset:         304
        .size:           8
        .value_kind:     hidden_global_offset_y
      - .offset:         312
        .size:           8
        .value_kind:     hidden_global_offset_z
      - .offset:         320
        .size:           2
        .value_kind:     hidden_grid_dims
      - .offset:         344
        .size:           8
        .value_kind:     hidden_multigrid_sync_arg
      - .offset:         376
        .size:           4
        .value_kind:     hidden_dynamic_lds_size
    .group_segment_fixed_size: 0
    .kernarg_segment_align: 8
    .kernarg_segment_size: 512
    .language:       OpenCL C
    .language_version:
      - 2
      - 0
    .max_flat_workgroup_size: 512
    .name:           _Z8fwd_mega4Args
    .private_segment_fixed_size: 0
    .sgpr_count:     108
    .sgpr_spill_count: 263
    .symbol:         _Z8fwd_mega4Args.kd
    .uniform_work_group_size: 1
    .uses_dynamic_stack: false
    .vgpr_count:     256
    .vgpr_spill_count: 0
    .wavefront_size: 64
